# RWKV scan rewritten (2 rows per lane on waves 0-3, LDS operands reloaded right after use); S5 scan LDS reads hoisted ahead of the recurrence chain
# speedup vs baseline: 1.0087x; 1.0087x over previous
.LBB0_262:
	s_or_b64 exec, exec, s[6:7]
	s_add_u32 s28, s70, 0x26140000
	s_addc_u32 s29, s71, 0
	v_bfe_u32 v72, v195, 3, 3
	s_mov_b32 s0, 0x3ffffff8
	v_mov_b64_e32 v[64:65], s[28:29]
	v_and_or_b32 v70, v176, s0, v72
	v_mad_u64_u32 v[64:65], s[0:1], v178, s67, v[64:65]
	v_mad_i32_i24 v65, v179, s67, v65
	v_lshl_add_u64 v[64:65], v[64:65], 0, v[198:199]
	global_load_dwordx4 v[120:123], v[64:65], off
	global_load_dwordx4 v[132:135], v[64:65], off offset:1024
	s_nop 0
	global_load_dwordx4 v[64:67], v[64:65], off offset:2048
	v_lshlrev_b32_e32 v69, 2, v69
	s_add_i32 s0, 0, 0x10000
	v_lshlrev_b32_e32 v71, 8, v176
	v_add_u32_e32 v197, s0, v69
	s_add_i32 s0, 0, 0x14000
	v_lshlrev_b32_e32 v70, 2, v70
	s_add_i32 s26, 0, 0x18000
	v_add_u32_e32 v177, 0, v69
	v_add3_u32 v212, s0, v71, v69
	v_add_u32_e32 v216, s0, v70
	v_lshlrev_b32_e32 v73, 8, v68
	v_add3_u32 v218, s26, v71, v69
	v_lshlrev_b32_e32 v69, 2, v176
	s_add_i32 s0, 0, 0x1c000
	v_cmp_eq_u32_e64 s[6:7], 0, v68
	v_add_u32_e32 v193, v177, v71
	v_add_u32_e32 v204, v197, v71
	v_cmp_eq_u32_e64 s[8:9], 7, v68
	v_add3_u32 v217, s26, v73, v70
	v_add_u32_e32 v219, s0, v69
	v_lshl_add_u64 v[70:71], s[70:71], 0, v[198:199]
	s_mov_b64 s[0:1], 0x37240000
	v_cmp_eq_u32_e64 s[10:11], 1, v68
	v_cmp_eq_u32_e64 s[12:13], 2, v68
	v_cmp_eq_u32_e64 s[14:15], 3, v68
	v_cmp_eq_u32_e64 s[16:17], 4, v68
	v_cmp_eq_u32_e64 s[18:19], 5, v68
	v_cmp_eq_u32_e64 s[20:21], 6, v68
	v_lshl_or_b32 v68, v195, 8, v245
	v_and_b32_e32 v69, 0xffffffe0, v69
	v_lshl_add_u64 v[180:181], v[70:71], 0, s[0:1]
	v_add_u32_e32 v68, v68, v69
	v_lshlrev_b32_e32 v70, 2, v72
	v_or_b32_e32 v68, v68, v70
	v_add_u32_e32 v220, s26, v68
	v_or_b32_e32 v68, v69, v70
	v_add_u32_e32 v221, 0, v68
	v_mov_b32_e32 v184, v199
	v_mov_b32_e32 v185, v199
	v_mov_b32_e32 v236, v199
	v_mov_b32_e32 v237, v199
	v_mov_b64_e32 v[248:249], v[236:237]
	v_mov_b64_e32 v[250:251], v[236:237]
	v_mov_b64_e32 v[252:253], v[236:237]
	s_waitcnt vmcnt(0)
	v_mov_b64_e32 v[96:97], v[108:109]
	v_mov_b64_e32 v[92:93], v[116:117]
	v_mov_b64_e32 v[88:89], v[128:129]
	v_mov_b64_e32 v[68:69], v[104:105]
	v_mov_b64_e32 v[72:73], v[112:113]
	v_mov_b64_e32 v[100:101], v[124:125]
	s_mov_b32 s4, 0
	v_add_u32_e32 v213, 0x4000, v177
	v_add_u32_e32 v214, 0xc000, v177
	v_add_u32_e32 v215, 0x8000, v177
	v_lshl_add_u64 v[182:183], s[28:29], 0, v[198:199]
	v_mov_b64_e32 v[186:187], v[184:185]
	v_mov_b64_e32 v[188:189], v[184:185]
	v_mov_b64_e32 v[190:191], v[184:185]
	v_mov_b64_e32 v[98:99], v[110:111]
	v_mov_b64_e32 v[94:95], v[118:119]
	v_mov_b64_e32 v[90:91], v[130:131]
	v_mov_b64_e32 v[70:71], v[106:107]
	v_mov_b64_e32 v[74:75], v[114:115]
	v_mov_b64_e32 v[102:103], v[126:127]
	s_waitcnt vmcnt(2)
	v_mov_b64_e32 v[84:85], v[120:121]
	s_waitcnt vmcnt(1)
	v_mov_b64_e32 v[80:81], v[132:133]
	s_waitcnt vmcnt(0)
	v_mov_b64_e32 v[78:79], v[66:67]
	v_mov_b64_e32 v[76:77], v[64:65]
	v_mov_b64_e32 v[82:83], v[134:135]
	v_mov_b64_e32 v[86:87], v[122:123]
	s_branch .LBB0_264
.LBB0_263:
	v_lshlrev_b32_e32 v112, 16, v64
	v_and_b32_e32 v113, 0xffff0000, v64
	v_lshlrev_b32_e32 v114, 16, v65
	v_and_b32_e32 v115, 0xffff0000, v65
	v_lshlrev_b32_e32 v116, 16, v66
	v_and_b32_e32 v117, 0xffff0000, v66
	v_lshlrev_b32_e32 v118, 16, v67
	v_and_b32_e32 v119, 0xffff0000, v67
	s_waitcnt lgkmcnt(0)
	s_barrier
	ds_read_b128 v[104:107], v218
	ds_read_b128 v[64:67], v218 offset:16
	ds_read_b128 v[108:111], v212
	s_lshl_b32 s52, s4, 6
	s_waitcnt vmcnt(1)
	v_mov_b64_e32 v[134:135], v[82:83]
	v_mov_b64_e32 v[130:131], v[90:91]
	s_waitcnt lgkmcnt(2)
	v_add_f32_e32 v120, 0, v104
	v_add_f32_e32 v120, v105, v120
	v_add_f32_e32 v120, v106, v120
	v_add_f32_e32 v120, v107, v120
	s_waitcnt lgkmcnt(1)
	v_add_f32_e32 v120, v64, v120
	v_add_f32_e32 v120, v65, v120
	v_add_f32_e32 v120, v66, v120
	v_add_f32_e32 v120, v67, v120
	s_cmp_eq_u32 s26, 32
	v_mov_b64_e32 v[132:133], v[80:81]
	v_add_f32_dpp v120, v120, v120 quad_perm:[1,0,3,2] row_mask:0xf bank_mask:0xf bound_ctrl:1
	v_mov_b64_e32 v[128:129], v[88:89]
	s_mov_b32 s4, s26
	v_add_f32_dpp v120, v120, v120 quad_perm:[2,3,0,1] row_mask:0xf bank_mask:0xf bound_ctrl:1
	s_nop 1
	v_add_f32_dpp v120, v120, v120 row_half_mirror row_mask:0xf bank_mask:0xf bound_ctrl:1
	v_mul_f32_e32 v120, 0x3c800000, v120
	v_pk_add_f32 v[104:105], v[104:105], v[120:121] op_sel_hi:[1,0] neg_lo:[0,1] neg_hi:[0,1]
	v_pk_add_f32 v[122:123], v[66:67], v[120:121] op_sel_hi:[1,0] neg_lo:[0,1] neg_hi:[0,1]
	v_pk_add_f32 v[124:125], v[64:65], v[120:121] op_sel_hi:[1,0] neg_lo:[0,1] neg_hi:[0,1]
	v_pk_add_f32 v[106:107], v[106:107], v[120:121] op_sel_hi:[1,0] neg_lo:[0,1] neg_hi:[0,1]
	v_pk_mul_f32 v[120:121], v[104:105], v[104:105]
	v_pk_mul_f32 v[126:127], v[106:107], v[106:107]
	v_add_f32_e32 v120, v120, v121
	v_add_f32_e32 v120, v126, v120
	v_pk_mul_f32 v[64:65], v[124:125], v[124:125]
	v_add_f32_e32 v120, v127, v120
	v_add_f32_e32 v64, v64, v120
	v_pk_mul_f32 v[66:67], v[122:123], v[122:123]
	v_add_f32_e32 v64, v65, v64
	v_add_f32_e32 v64, v66, v64
	v_add_f32_e32 v64, v67, v64
	ds_read_b32 v126, v219
	s_nop 0
	v_add_f32_dpp v64, v64, v64 quad_perm:[1,0,3,2] row_mask:0xf bank_mask:0xf bound_ctrl:1
	s_nop 1
	v_add_f32_dpp v64, v64, v64 quad_perm:[2,3,0,1] row_mask:0xf bank_mask:0xf bound_ctrl:1
	s_nop 1
	v_add_f32_dpp v64, v64, v64 row_half_mirror row_mask:0xf bank_mask:0xf bound_ctrl:1
	v_fmamk_f32 v64, v64, 0x3c800000, v240
	v_rsq_f32_e32 v120, v64
	ds_read_b128 v[64:67], v212 offset:16
	v_pk_mul_f32 v[104:105], v[104:105], v[120:121] op_sel_hi:[1,0]
	s_nop 0
	v_pk_fma_f32 v[104:105], v[52:53], v[104:105], v[60:61]
	v_pk_mul_f32 v[106:107], v[106:107], v[120:121] op_sel_hi:[1,0]
	s_waitcnt lgkmcnt(1)
	v_pk_fma_f32 v[104:105], v[108:109], v[126:127], v[104:105] op_sel_hi:[1,0,1]
	v_pk_mul_f32 v[108:109], v[124:125], v[120:121] op_sel_hi:[1,0]
	v_pk_fma_f32 v[106:107], v[54:55], v[106:107], v[62:63]
	v_pk_fma_f32 v[108:109], v[48:49], v[108:109], v[56:57]
	v_pk_mul_f32 v[104:105], v[104:105], v[112:113]
	s_waitcnt lgkmcnt(0)
	v_pk_fma_f32 v[64:65], v[64:65], v[126:127], v[108:109] op_sel_hi:[1,0,1]
	v_pk_fma_f32 v[106:107], v[110:111], v[126:127], v[106:107] op_sel_hi:[1,0,1]
	v_pk_mul_f32 v[108:109], v[64:65], v[116:117]
	v_pk_mul_f32 v[64:65], v[122:123], v[120:121] op_sel_hi:[1,0]
	v_lshl_add_u64 v[112:113], v[178:179], 0, s[52:53]
	v_pk_fma_f32 v[64:65], v[50:51], v[64:65], v[58:59]
	v_pk_mul_f32 v[106:107], v[106:107], v[114:115]
	v_pk_fma_f32 v[64:65], v[66:67], v[126:127], v[64:65] op_sel_hi:[1,0,1]
	v_cvt_pk_bf16_f32 v66, v108, v109
	v_pk_mul_f32 v[110:111], v[64:65], v[118:119]
	v_cvt_pk_bf16_f32 v64, v104, v105
	v_lshlrev_b64 v[104:105], 12, v[112:113]
	v_cvt_pk_bf16_f32 v65, v106, v107
	v_cvt_pk_bf16_f32 v67, v110, v111
	v_lshl_add_u64 v[104:105], v[180:181], 0, v[104:105]
	global_store_dwordx4 v[104:105], v[64:67], off
	v_mov_b64_e32 v[122:123], v[86:87]
	v_mov_b64_e32 v[110:111], v[98:99]
	s_waitcnt vmcnt(1)
	v_mov_b64_e32 v[64:65], v[76:77]
	v_mov_b64_e32 v[118:119], v[94:95]
	v_mov_b64_e32 v[106:107], v[70:71]
	v_mov_b64_e32 v[114:115], v[74:75]
	v_mov_b64_e32 v[126:127], v[102:103]
	v_mov_b64_e32 v[66:67], v[78:79]
	v_mov_b64_e32 v[120:121], v[84:85]
	v_mov_b64_e32 v[108:109], v[96:97]
	v_mov_b64_e32 v[116:117], v[92:93]
	v_mov_b64_e32 v[104:105], v[68:69]
	v_mov_b64_e32 v[112:113], v[72:73]
	v_mov_b64_e32 v[124:125], v[100:101]
	s_cbranch_scc1 .LBB0_274

.LBB0_268:
	v_lshlrev_b32_e32 v136, 16, v124
	v_and_b32_e32 v137, 0xffff0000, v124
	v_lshlrev_b32_e32 v138, 16, v128
	v_and_b32_e32 v139, 0xffff0000, v128
	v_lshlrev_b32_e32 v124, 16, v125
	v_and_b32_e32 v125, 0xffff0000, v125
	v_lshlrev_b32_e32 v128, 16, v129
	v_and_b32_e32 v129, 0xffff0000, v129
	v_pk_add_f32 v[138:139], v[138:139], v[136:137] neg_lo:[0,1] neg_hi:[0,1]
	v_pk_add_f32 v[128:129], v[128:129], v[124:125] neg_lo:[0,1] neg_hi:[0,1]
	v_pk_fma_f32 v[136:137], v[12:13], v[138:139], v[136:137]
	v_pk_fma_f32 v[138:139], v[14:15], v[128:129], v[124:125]
	v_lshlrev_b32_e32 v124, 16, v126
	v_and_b32_e32 v125, 0xffff0000, v126
	v_lshlrev_b32_e32 v128, 16, v130
	v_and_b32_e32 v129, 0xffff0000, v130
	v_pk_add_f32 v[128:129], v[128:129], v[124:125] neg_lo:[0,1] neg_hi:[0,1]
	v_lshlrev_b32_e32 v126, 16, v127
	v_pk_fma_f32 v[124:125], v[8:9], v[128:129], v[124:125]
	v_and_b32_e32 v127, 0xffff0000, v127
	v_lshlrev_b32_e32 v128, 16, v131
	v_and_b32_e32 v129, 0xffff0000, v131
	v_pk_add_f32 v[128:129], v[128:129], v[126:127] neg_lo:[0,1] neg_hi:[0,1]
	v_lshlrev_b32_e32 v130, 16, v116
	v_pk_fma_f32 v[126:127], v[10:11], v[128:129], v[126:127]
	v_lshlrev_b32_e32 v128, 16, v112
	v_and_b32_e32 v129, 0xffff0000, v112
	v_and_b32_e32 v131, 0xffff0000, v116
	v_lshlrev_b32_e32 v112, 16, v113
	v_and_b32_e32 v113, 0xffff0000, v113
	v_lshlrev_b32_e32 v116, 16, v117
	v_and_b32_e32 v117, 0xffff0000, v117
	v_pk_add_f32 v[130:131], v[130:131], v[128:129] neg_lo:[0,1] neg_hi:[0,1]
	v_pk_add_f32 v[116:117], v[116:117], v[112:113] neg_lo:[0,1] neg_hi:[0,1]
	v_pk_fma_f32 v[142:143], v[36:37], v[130:131], v[128:129]
	v_lshlrev_b32_e32 v128, 16, v132
	v_and_b32_e32 v129, 0xffff0000, v132
	v_pk_fma_f32 v[116:117], v[38:39], v[116:117], v[112:113]
	v_lshlrev_b32_e32 v130, 16, v133
	v_and_b32_e32 v131, 0xffff0000, v133
	v_lshlrev_b32_e32 v112, 16, v114
	v_and_b32_e32 v113, 0xffff0000, v114
	v_lshlrev_b32_e32 v132, 16, v118
	v_and_b32_e32 v133, 0xffff0000, v118
	v_pk_add_f32 v[132:133], v[132:133], v[112:113] neg_lo:[0,1] neg_hi:[0,1]
	v_lshlrev_b32_e32 v114, 16, v119
	v_pk_fma_f32 v[146:147], v[32:33], v[132:133], v[112:113]
	v_lshlrev_b32_e32 v112, 16, v115
	v_and_b32_e32 v113, 0xffff0000, v115
	v_and_b32_e32 v115, 0xffff0000, v119
	v_pk_add_f32 v[114:115], v[114:115], v[112:113] neg_lo:[0,1] neg_hi:[0,1]
	v_pk_mul_f32 v[140:141], v[28:29], v[142:143]
	v_pk_fma_f32 v[118:119], v[34:35], v[114:115], v[112:113]
	v_pk_add_f32 v[112:113], v[128:129], -1.0 op_sel_hi:[1,0]
	v_lshlrev_b32_e32 v132, 16, v134
	v_pk_fma_f32 v[112:113], v[44:45], v[112:113], 1.0 op_sel_hi:[1,1,0]
	v_and_b32_e32 v133, 0xffff0000, v134
	v_pk_mul_f32 v[112:113], v[112:113], v[142:143]
	v_pk_mul_f32 v[142:143], v[30:31], v[116:117]
	v_pk_mul_f32 v[114:115], v[136:137], v[112:113]
	v_pk_mul_f32 v[148:149], v[140:141], v[140:141]
	v_fma_f32 v158, v4, v114, 0
	v_fmac_f32_e32 v158, v5, v115
	v_pk_add_f32 v[114:115], v[130:131], -1.0 op_sel_hi:[1,0]
	v_lshlrev_b32_e32 v134, 16, v135
	v_pk_fma_f32 v[114:115], v[46:47], v[114:115], 1.0 op_sel_hi:[1,1,0]
	v_and_b32_e32 v135, 0xffff0000, v135
	v_pk_mul_f32 v[114:115], v[114:115], v[116:117]
	v_pk_mul_f32 v[150:151], v[142:143], v[142:143]
	v_pk_mul_f32 v[116:117], v[138:139], v[114:115]
	v_add_f32_e32 v148, v148, v149
	v_fmac_f32_e32 v158, v6, v116
	v_fmac_f32_e32 v158, v7, v117
	v_pk_add_f32 v[116:117], v[132:133], -1.0 op_sel_hi:[1,0]
	v_pk_mul_f32 v[144:145], v[24:25], v[146:147]
	v_pk_fma_f32 v[116:117], v[40:41], v[116:117], 1.0 op_sel_hi:[1,1,0]
	v_pk_add_f32 v[154:155], v[134:135], -1.0 op_sel_hi:[1,0]
	v_pk_mul_f32 v[116:117], v[116:117], v[146:147]
	v_add_f32_e32 v148, v150, v148
	v_pk_mul_f32 v[146:147], v[124:125], v[116:117]
	v_pk_mul_f32 v[152:153], v[144:145], v[144:145]
	v_fmac_f32_e32 v158, v0, v146
	v_add_f32_e32 v148, v151, v148
	v_pk_fma_f32 v[150:151], v[42:43], v[154:155], 1.0 op_sel_hi:[1,1,0]
	v_fmac_f32_e32 v158, v1, v147
	v_pk_mul_f32 v[146:147], v[26:27], v[118:119]
	v_add_f32_e32 v148, v152, v148
	v_pk_mul_f32 v[118:119], v[150:151], v[118:119]
	v_pk_mul_f32 v[156:157], v[146:147], v[146:147]
	v_add_f32_e32 v148, v153, v148
	v_pk_mul_f32 v[150:151], v[126:127], v[118:119]
	v_add_f32_e32 v148, v156, v148
	v_fmac_f32_e32 v158, v2, v150
	v_add_f32_e32 v148, v157, v148
	v_fmac_f32_e32 v158, v3, v151
	s_nop 0
	v_add_f32_dpp v148, v148, v148 quad_perm:[1,0,3,2] row_mask:0xf bank_mask:0xf bound_ctrl:1
	v_add_f32_dpp v150, v158, v158 quad_perm:[1,0,3,2] row_mask:0xf bank_mask:0xf bound_ctrl:1
	s_nop 0
	v_add_f32_dpp v148, v148, v148 quad_perm:[2,3,0,1] row_mask:0xf bank_mask:0xf bound_ctrl:1
	v_add_f32_dpp v150, v150, v150 quad_perm:[2,3,0,1] row_mask:0xf bank_mask:0xf bound_ctrl:1
	s_nop 0
	v_mov_b32_dpp v149, v148 row_half_mirror row_mask:0xf bank_mask:0xf bound_ctrl:1
	v_mov_b32_dpp v151, v150 row_half_mirror row_mask:0xf bank_mask:0xf bound_ctrl:1
	s_and_saveexec_b64 s[28:29], s[6:7]
	v_add_f32_e32 v150, v150, v151
	ds_write_b32 v219, v150
	s_or_b64 exec, exec, s[28:29]
	v_add_f32_e32 v148, v148, v149
	v_max_f32_e32 v148, 0x179abe15, v148
	v_rsq_f32_e32 v148, v148
	v_lshlrev_b32_e32 v156, 16, v123
	v_and_b32_e32 v157, 0xffff0000, v123
	v_mul_f32_e32 v149, 0x3fb8aa3b, v156
	v_lshlrev_b32_e32 v150, 16, v120
	v_and_b32_e32 v151, 0xffff0000, v120
	v_lshlrev_b32_e32 v152, 16, v121
	v_and_b32_e32 v153, 0xffff0000, v121
	v_lshlrev_b32_e32 v154, 16, v122
	v_and_b32_e32 v155, 0xffff0000, v122
	v_pk_mul_f32 v[140:141], v[140:141], v[148:149] op_sel_hi:[1,0]
	v_pk_mul_f32 v[142:143], v[142:143], v[148:149] op_sel_hi:[1,0]
	v_pk_mul_f32 v[144:145], v[144:145], v[148:149] op_sel_hi:[1,0]
	v_pk_mul_f32 v[146:147], v[146:147], v[148:149] op_sel_hi:[1,0]
	v_mul_f32_e32 v148, 0x3fb8aa3b, v157
	v_mul_f32_e32 v120, 0x3fb8aa3b, v150
	v_mul_f32_e32 v121, 0x3fb8aa3b, v151
	v_mul_f32_e32 v122, 0x3fb8aa3b, v152
	v_mul_f32_e32 v123, 0x3fb8aa3b, v153
	v_mul_f32_e32 v150, 0x3fb8aa3b, v154
	v_mul_f32_e32 v151, 0x3fb8aa3b, v155
	v_exp_f32_e32 v152, v149
	v_exp_f32_e32 v153, v148
	v_lshlrev_b32_e32 v148, 16, v104
	v_and_b32_e32 v149, 0xffff0000, v104
	v_lshlrev_b32_e32 v154, 16, v108
	v_and_b32_e32 v155, 0xffff0000, v108
	v_lshlrev_b32_e32 v104, 16, v105
	v_and_b32_e32 v105, 0xffff0000, v105
	v_lshlrev_b32_e32 v108, 16, v109
	v_and_b32_e32 v109, 0xffff0000, v109
	v_pk_add_f32 v[108:109], v[108:109], v[104:105] neg_lo:[0,1] neg_hi:[0,1]
	v_exp_f32_e32 v120, v120
	v_pk_fma_f32 v[156:157], v[18:19], v[108:109], v[104:105]
	v_lshlrev_b32_e32 v104, 16, v106
	v_and_b32_e32 v105, 0xffff0000, v106
	v_lshlrev_b32_e32 v108, 16, v110
	v_and_b32_e32 v109, 0xffff0000, v110
	v_pk_add_f32 v[108:109], v[108:109], v[104:105] neg_lo:[0,1] neg_hi:[0,1]
	v_lshlrev_b32_e32 v106, 16, v107
	v_pk_fma_f32 v[104:105], v[20:21], v[108:109], v[104:105]
	v_and_b32_e32 v107, 0xffff0000, v107
	v_lshlrev_b32_e32 v108, 16, v111
	v_and_b32_e32 v109, 0xffff0000, v111
	v_exp_f32_e32 v121, v121
	v_exp_f32_e32 v122, v122
	v_exp_f32_e32 v123, v123
	v_pk_add_f32 v[108:109], v[108:109], v[106:107] neg_lo:[0,1] neg_hi:[0,1]
	v_exp_f32_e32 v150, v150
	v_exp_f32_e32 v151, v151
	v_pk_fma_f32 v[106:107], v[22:23], v[108:109], v[106:107]
	v_pk_mul_f32 v[108:109], v[140:141], v[128:129]
	v_pk_mul_f32 v[110:111], v[142:143], v[130:131]
	v_pk_add_f32 v[154:155], v[154:155], v[148:149] neg_lo:[0,1] neg_hi:[0,1]
	ds_write_b128 v193, v[136:139]
	ds_write_b128 v193, v[124:127] offset:16
	ds_write_b128 v193, v[120:123] offset:16384
	ds_write_b128 v193, v[150:153] offset:16400
	ds_write_b128 v193, v[112:115] offset:32768
	ds_write_b128 v193, v[116:119] offset:32784
	ds_write_b128 v193, v[140:143] offset:49152
	ds_write_b128 v193, v[144:147] offset:49168
	ds_write_b128 v204, v[108:111]
	v_pk_mul_f32 v[108:109], v[144:145], v[132:133]
	v_pk_mul_f32 v[110:111], v[146:147], v[134:135]
	v_mov_b32_e32 v224, 0
	v_pk_fma_f32 v[154:155], v[16:17], v[154:155], v[148:149]
	ds_write_b128 v204, v[108:111] offset:16
	ds_write_b128 v212, v[154:157]
	ds_write_b128 v212, v[104:107] offset:16
	s_waitcnt lgkmcnt(0)
	s_barrier
	v_readfirstlane_b32 s0, v238
	s_nop 1
	s_cmpk_ge_u32 s0, 0x100
	s_cbranch_scc1 .LBB0_263
	s_mov_b32 s27, 0
	v_mov_b32_e32 v222, v177
	v_mov_b32_e32 v223, v197
	v_mov_b32_e32 v226, v216
	v_add_u32_e32 v227, 0x8000, v217
	ds_read_b128 v[112:115], v222 offset:49152
	ds_read_b128 v[116:119], v222 offset:49168
	ds_read_b128 v[120:123], v223 offset:0
	ds_read_b128 v[124:127], v223 offset:16
	ds_read_b128 v[128:131], v222 offset:32768
	ds_read_b128 v[132:135], v222 offset:32784
	ds_read_b32 v144, v226 offset:0
	ds_read_b32 v146, v226 offset:128
	ds_read_b128 v[104:107], v222 offset:16384
	ds_read_b128 v[108:111], v222 offset:16400
	ds_read_b128 v[136:139], v222 offset:0
	ds_read_b128 v[140:143], v222 offset:16
	v_mov_b32_e32 v156, 0
	v_mov_b32_e32 v157, 0
	v_mov_b32_e32 v158, 0
	v_mov_b32_e32 v159, 0
	v_mov_b32_e32 v224, 0
	v_mov_b32_e32 v225, 0
.Lrwkv_scan_loop:
	s_waitcnt lgkmcnt(10)
	v_pk_mul_f32 v[148:149], v[184:185], v[112:113]
	v_pk_mul_f32 v[150:151], v[236:237], v[112:113]
	v_pk_fma_f32 v[148:149], v[186:187], v[114:115], v[148:149]
	v_pk_fma_f32 v[150:151], v[248:249], v[114:115], v[150:151]
	v_pk_fma_f32 v[148:149], v[188:189], v[116:117], v[148:149]
	v_pk_fma_f32 v[150:151], v[250:251], v[116:117], v[150:151]
	v_pk_fma_f32 v[148:149], v[190:191], v[118:119], v[148:149]
	v_pk_fma_f32 v[150:151], v[252:253], v[118:119], v[150:151]
	ds_read_b128 v[112:115], v222 offset:49408
	ds_read_b128 v[116:119], v222 offset:49424
	v_add_f32_e32 v152, v148, v149
	v_add_f32_e32 v153, v156, v157
	v_add_f32_e32 v154, v150, v151
	v_add_f32_e32 v155, v158, v159
	v_add_f32_dpp v152, v152, v152 quad_perm:[1,0,3,2] row_mask:0xf bank_mask:0xf bound_ctrl:1
	v_add_f32_dpp v153, v153, v153 quad_perm:[1,0,3,2] row_mask:0xf bank_mask:0xf bound_ctrl:1
	v_add_f32_dpp v154, v154, v154 quad_perm:[1,0,3,2] row_mask:0xf bank_mask:0xf bound_ctrl:1
	v_add_f32_dpp v155, v155, v155 quad_perm:[1,0,3,2] row_mask:0xf bank_mask:0xf bound_ctrl:1
	v_add_f32_dpp v152, v152, v152 quad_perm:[2,3,0,1] row_mask:0xf bank_mask:0xf bound_ctrl:1
	v_add_f32_dpp v153, v153, v153 quad_perm:[2,3,0,1] row_mask:0xf bank_mask:0xf bound_ctrl:1
	v_add_f32_dpp v154, v154, v154 quad_perm:[2,3,0,1] row_mask:0xf bank_mask:0xf bound_ctrl:1
	v_add_f32_dpp v155, v155, v155 quad_perm:[2,3,0,1] row_mask:0xf bank_mask:0xf bound_ctrl:1
	v_add_f32_dpp v152, v152, v152 row_half_mirror row_mask:0xf bank_mask:0xf bound_ctrl:1
	v_add_f32_dpp v153, v153, v153 row_half_mirror row_mask:0xf bank_mask:0xf bound_ctrl:1
	v_add_f32_dpp v154, v154, v154 row_half_mirror row_mask:0xf bank_mask:0xf bound_ctrl:1
	v_add_f32_dpp v155, v155, v155 row_half_mirror row_mask:0xf bank_mask:0xf bound_ctrl:1
	v_cndmask_b32_e64 v224, v224, v153, s[8:9]
	v_cndmask_b32_e64 v225, v225, v155, s[8:9]
	ds_write_b32 v227, v224
	ds_write_b32 v227, v225 offset:128
	s_waitcnt lgkmcnt(10)
	v_pk_mul_f32 v[160:161], v[120:121], v[152:153] op_sel_hi:[1,0] neg_lo:[0,1] neg_hi:[0,1]
	v_pk_mul_f32 v[168:169], v[120:121], v[154:155] op_sel_hi:[1,0] neg_lo:[0,1] neg_hi:[0,1]
	v_pk_mul_f32 v[162:163], v[122:123], v[152:153] op_sel_hi:[1,0] neg_lo:[0,1] neg_hi:[0,1]
	v_pk_mul_f32 v[170:171], v[122:123], v[154:155] op_sel_hi:[1,0] neg_lo:[0,1] neg_hi:[0,1]
	v_pk_mul_f32 v[164:165], v[124:125], v[152:153] op_sel_hi:[1,0] neg_lo:[0,1] neg_hi:[0,1]
	v_pk_mul_f32 v[172:173], v[124:125], v[154:155] op_sel_hi:[1,0] neg_lo:[0,1] neg_hi:[0,1]
	v_pk_mul_f32 v[166:167], v[126:127], v[152:153] op_sel_hi:[1,0] neg_lo:[0,1] neg_hi:[0,1]
	v_pk_mul_f32 v[174:175], v[126:127], v[154:155] op_sel_hi:[1,0] neg_lo:[0,1] neg_hi:[0,1]
	v_add_u32_e32 v227, s27, v217
	ds_read_b128 v[120:123], v223 offset:256
	ds_read_b128 v[124:127], v223 offset:272
	s_waitcnt lgkmcnt(8)
	v_pk_fma_f32 v[160:161], v[144:145], v[128:129], v[160:161] op_sel_hi:[0,1,1]
	v_pk_fma_f32 v[168:169], v[146:147], v[128:129], v[168:169] op_sel_hi:[0,1,1]
	v_pk_fma_f32 v[162:163], v[144:145], v[130:131], v[162:163] op_sel_hi:[0,1,1]
	v_pk_fma_f32 v[170:171], v[146:147], v[130:131], v[170:171] op_sel_hi:[0,1,1]
	v_pk_fma_f32 v[164:165], v[144:145], v[132:133], v[164:165] op_sel_hi:[0,1,1]
	v_pk_fma_f32 v[172:173], v[146:147], v[132:133], v[172:173] op_sel_hi:[0,1,1]
	v_pk_fma_f32 v[166:167], v[144:145], v[134:135], v[166:167] op_sel_hi:[0,1,1]
	v_pk_fma_f32 v[174:175], v[146:147], v[134:135], v[174:175] op_sel_hi:[0,1,1]
	ds_read_b128 v[128:131], v222 offset:33024
	ds_read_b128 v[132:135], v222 offset:33040
	ds_read_b32 v144, v226 offset:256
	ds_read_b32 v146, v226 offset:384
	s_waitcnt lgkmcnt(10)
	v_pk_fma_f32 v[184:185], v[184:185], v[104:105], v[160:161]
	v_pk_fma_f32 v[236:237], v[236:237], v[104:105], v[168:169]
	v_pk_fma_f32 v[186:187], v[186:187], v[106:107], v[162:163]
	v_pk_fma_f32 v[248:249], v[248:249], v[106:107], v[170:171]
	v_pk_fma_f32 v[188:189], v[188:189], v[108:109], v[164:165]
	v_pk_fma_f32 v[250:251], v[250:251], v[108:109], v[172:173]
	v_pk_fma_f32 v[190:191], v[190:191], v[110:111], v[166:167]
	v_pk_fma_f32 v[252:253], v[252:253], v[110:111], v[174:175]
	ds_read_b128 v[104:107], v222 offset:16640
	ds_read_b128 v[108:111], v222 offset:16656
	s_waitcnt lgkmcnt(10)
	v_pk_mul_f32 v[156:157], v[184:185], v[136:137]
	v_pk_mul_f32 v[158:159], v[236:237], v[136:137]
	v_pk_fma_f32 v[156:157], v[186:187], v[138:139], v[156:157]
	v_pk_fma_f32 v[158:159], v[248:249], v[138:139], v[158:159]
	v_pk_fma_f32 v[156:157], v[188:189], v[140:141], v[156:157]
	v_pk_fma_f32 v[158:159], v[250:251], v[140:141], v[158:159]
	v_pk_fma_f32 v[156:157], v[190:191], v[142:143], v[156:157]
	v_pk_fma_f32 v[158:159], v[252:253], v[142:143], v[158:159]
	ds_read_b128 v[136:139], v222 offset:256
	ds_read_b128 v[140:143], v222 offset:272
	s_waitcnt lgkmcnt(10)
	v_pk_mul_f32 v[148:149], v[184:185], v[112:113]
	v_pk_mul_f32 v[150:151], v[236:237], v[112:113]
	v_pk_fma_f32 v[148:149], v[186:187], v[114:115], v[148:149]
	v_pk_fma_f32 v[150:151], v[248:249], v[114:115], v[150:151]
	v_pk_fma_f32 v[148:149], v[188:189], v[116:117], v[148:149]
	v_pk_fma_f32 v[150:151], v[250:251], v[116:117], v[150:151]
	v_pk_fma_f32 v[148:149], v[190:191], v[118:119], v[148:149]
	v_pk_fma_f32 v[150:151], v[252:253], v[118:119], v[150:151]
	ds_read_b128 v[112:115], v222 offset:49664
	ds_read_b128 v[116:119], v222 offset:49680
	v_add_f32_e32 v152, v148, v149
	v_add_f32_e32 v153, v156, v157
	v_add_f32_e32 v154, v150, v151
	v_add_f32_e32 v155, v158, v159
	v_add_f32_dpp v152, v152, v152 quad_perm:[1,0,3,2] row_mask:0xf bank_mask:0xf bound_ctrl:1
	v_add_f32_dpp v153, v153, v153 quad_perm:[1,0,3,2] row_mask:0xf bank_mask:0xf bound_ctrl:1
	v_add_f32_dpp v154, v154, v154 quad_perm:[1,0,3,2] row_mask:0xf bank_mask:0xf bound_ctrl:1
	v_add_f32_dpp v155, v155, v155 quad_perm:[1,0,3,2] row_mask:0xf bank_mask:0xf bound_ctrl:1
	v_add_f32_dpp v152, v152, v152 quad_perm:[2,3,0,1] row_mask:0xf bank_mask:0xf bound_ctrl:1
	v_add_f32_dpp v153, v153, v153 quad_perm:[2,3,0,1] row_mask:0xf bank_mask:0xf bound_ctrl:1
	v_add_f32_dpp v154, v154, v154 quad_perm:[2,3,0,1] row_mask:0xf bank_mask:0xf bound_ctrl:1
	v_add_f32_dpp v155, v155, v155 quad_perm:[2,3,0,1] row_mask:0xf bank_mask:0xf bound_ctrl:1
	v_add_f32_dpp v152, v152, v152 row_half_mirror row_mask:0xf bank_mask:0xf bound_ctrl:1
	v_add_f32_dpp v153, v153, v153 row_half_mirror row_mask:0xf bank_mask:0xf bound_ctrl:1
	v_add_f32_dpp v154, v154, v154 row_half_mirror row_mask:0xf bank_mask:0xf bound_ctrl:1
	v_add_f32_dpp v155, v155, v155 row_half_mirror row_mask:0xf bank_mask:0xf bound_ctrl:1
	v_cndmask_b32_e64 v224, v224, v153, s[6:7]
	v_cndmask_b32_e64 v225, v225, v155, s[6:7]
	s_waitcnt lgkmcnt(10)
	v_pk_mul_f32 v[160:161], v[120:121], v[152:153] op_sel_hi:[1,0] neg_lo:[0,1] neg_hi:[0,1]
	v_pk_mul_f32 v[168:169], v[120:121], v[154:155] op_sel_hi:[1,0] neg_lo:[0,1] neg_hi:[0,1]
	v_pk_mul_f32 v[162:163], v[122:123], v[152:153] op_sel_hi:[1,0] neg_lo:[0,1] neg_hi:[0,1]
	v_pk_mul_f32 v[170:171], v[122:123], v[154:155] op_sel_hi:[1,0] neg_lo:[0,1] neg_hi:[0,1]
	v_pk_mul_f32 v[164:165], v[124:125], v[152:153] op_sel_hi:[1,0] neg_lo:[0,1] neg_hi:[0,1]
	v_pk_mul_f32 v[172:173], v[124:125], v[154:155] op_sel_hi:[1,0] neg_lo:[0,1] neg_hi:[0,1]
	v_pk_mul_f32 v[166:167], v[126:127], v[152:153] op_sel_hi:[1,0] neg_lo:[0,1] neg_hi:[0,1]
	v_pk_mul_f32 v[174:175], v[126:127], v[154:155] op_sel_hi:[1,0] neg_lo:[0,1] neg_hi:[0,1]
	ds_read_b128 v[120:123], v223 offset:512
	ds_read_b128 v[124:127], v223 offset:528
	s_waitcnt lgkmcnt(8)
	v_pk_fma_f32 v[160:161], v[144:145], v[128:129], v[160:161] op_sel_hi:[0,1,1]
	v_pk_fma_f32 v[168:169], v[146:147], v[128:129], v[168:169] op_sel_hi:[0,1,1]
	v_pk_fma_f32 v[162:163], v[144:145], v[130:131], v[162:163] op_sel_hi:[0,1,1]
	v_pk_fma_f32 v[170:171], v[146:147], v[130:131], v[170:171] op_sel_hi:[0,1,1]
	v_pk_fma_f32 v[164:165], v[144:145], v[132:133], v[164:165] op_sel_hi:[0,1,1]
	v_pk_fma_f32 v[172:173], v[146:147], v[132:133], v[172:173] op_sel_hi:[0,1,1]
	v_pk_fma_f32 v[166:167], v[144:145], v[134:135], v[166:167] op_sel_hi:[0,1,1]
	v_pk_fma_f32 v[174:175], v[146:147], v[134:135], v[174:175] op_sel_hi:[0,1,1]
	ds_read_b128 v[128:131], v222 offset:33280
	ds_read_b128 v[132:135], v222 offset:33296
	ds_read_b32 v144, v226 offset:512
	ds_read_b32 v146, v226 offset:640
	s_waitcnt lgkmcnt(10)
	v_pk_fma_f32 v[184:185], v[184:185], v[104:105], v[160:161]
	v_pk_fma_f32 v[236:237], v[236:237], v[104:105], v[168:169]
	v_pk_fma_f32 v[186:187], v[186:187], v[106:107], v[162:163]
	v_pk_fma_f32 v[248:249], v[248:249], v[106:107], v[170:171]
	v_pk_fma_f32 v[188:189], v[188:189], v[108:109], v[164:165]
	v_pk_fma_f32 v[250:251], v[250:251], v[108:109], v[172:173]
	v_pk_fma_f32 v[190:191], v[190:191], v[110:111], v[166:167]
	v_pk_fma_f32 v[252:253], v[252:253], v[110:111], v[174:175]
	ds_read_b128 v[104:107], v222 offset:16896
	ds_read_b128 v[108:111], v222 offset:16912
	s_waitcnt lgkmcnt(10)
	v_pk_mul_f32 v[156:157], v[184:185], v[136:137]
	v_pk_mul_f32 v[158:159], v[236:237], v[136:137]
	v_pk_fma_f32 v[156:157], v[186:187], v[138:139], v[156:157]
	v_pk_fma_f32 v[158:159], v[248:249], v[138:139], v[158:159]
	v_pk_fma_f32 v[156:157], v[188:189], v[140:141], v[156:157]
	v_pk_fma_f32 v[158:159], v[250:251], v[140:141], v[158:159]
	v_pk_fma_f32 v[156:157], v[190:191], v[142:143], v[156:157]
	v_pk_fma_f32 v[158:159], v[252:253], v[142:143], v[158:159]
	ds_read_b128 v[136:139], v222 offset:512
	ds_read_b128 v[140:143], v222 offset:528
	s_waitcnt lgkmcnt(10)
	v_pk_mul_f32 v[148:149], v[184:185], v[112:113]
	v_pk_mul_f32 v[150:151], v[236:237], v[112:113]
	v_pk_fma_f32 v[148:149], v[186:187], v[114:115], v[148:149]
	v_pk_fma_f32 v[150:151], v[248:249], v[114:115], v[150:151]
	v_pk_fma_f32 v[148:149], v[188:189], v[116:117], v[148:149]
	v_pk_fma_f32 v[150:151], v[250:251], v[116:117], v[150:151]
	v_pk_fma_f32 v[148:149], v[190:191], v[118:119], v[148:149]
	v_pk_fma_f32 v[150:151], v[252:253], v[118:119], v[150:151]
	ds_read_b128 v[112:115], v222 offset:49920
	ds_read_b128 v[116:119], v222 offset:49936
	v_add_f32_e32 v152, v148, v149
	v_add_f32_e32 v153, v156, v157
	v_add_f32_e32 v154, v150, v151
	v_add_f32_e32 v155, v158, v159
	v_add_f32_dpp v152, v152, v152 quad_perm:[1,0,3,2] row_mask:0xf bank_mask:0xf bound_ctrl:1
	v_add_f32_dpp v153, v153, v153 quad_perm:[1,0,3,2] row_mask:0xf bank_mask:0xf bound_ctrl:1
	v_add_f32_dpp v154, v154, v154 quad_perm:[1,0,3,2] row_mask:0xf bank_mask:0xf bound_ctrl:1
	v_add_f32_dpp v155, v155, v155 quad_perm:[1,0,3,2] row_mask:0xf bank_mask:0xf bound_ctrl:1
	v_add_f32_dpp v152, v152, v152 quad_perm:[2,3,0,1] row_mask:0xf bank_mask:0xf bound_ctrl:1
	v_add_f32_dpp v153, v153, v153 quad_perm:[2,3,0,1] row_mask:0xf bank_mask:0xf bound_ctrl:1
	v_add_f32_dpp v154, v154, v154 quad_perm:[2,3,0,1] row_mask:0xf bank_mask:0xf bound_ctrl:1
	v_add_f32_dpp v155, v155, v155 quad_perm:[2,3,0,1] row_mask:0xf bank_mask:0xf bound_ctrl:1
	v_add_f32_dpp v152, v152, v152 row_half_mirror row_mask:0xf bank_mask:0xf bound_ctrl:1
	v_add_f32_dpp v153, v153, v153 row_half_mirror row_mask:0xf bank_mask:0xf bound_ctrl:1
	v_add_f32_dpp v154, v154, v154 row_half_mirror row_mask:0xf bank_mask:0xf bound_ctrl:1
	v_add_f32_dpp v155, v155, v155 row_half_mirror row_mask:0xf bank_mask:0xf bound_ctrl:1
	v_cndmask_b32_e64 v224, v224, v153, s[10:11]
	v_cndmask_b32_e64 v225, v225, v155, s[10:11]
	s_waitcnt lgkmcnt(10)
	v_pk_mul_f32 v[160:161], v[120:121], v[152:153] op_sel_hi:[1,0] neg_lo:[0,1] neg_hi:[0,1]
	v_pk_mul_f32 v[168:169], v[120:121], v[154:155] op_sel_hi:[1,0] neg_lo:[0,1] neg_hi:[0,1]
	v_pk_mul_f32 v[162:163], v[122:123], v[152:153] op_sel_hi:[1,0] neg_lo:[0,1] neg_hi:[0,1]
	v_pk_mul_f32 v[170:171], v[122:123], v[154:155] op_sel_hi:[1,0] neg_lo:[0,1] neg_hi:[0,1]
	v_pk_mul_f32 v[164:165], v[124:125], v[152:153] op_sel_hi:[1,0] neg_lo:[0,1] neg_hi:[0,1]
	v_pk_mul_f32 v[172:173], v[124:125], v[154:155] op_sel_hi:[1,0] neg_lo:[0,1] neg_hi:[0,1]
	v_pk_mul_f32 v[166:167], v[126:127], v[152:153] op_sel_hi:[1,0] neg_lo:[0,1] neg_hi:[0,1]
	v_pk_mul_f32 v[174:175], v[126:127], v[154:155] op_sel_hi:[1,0] neg_lo:[0,1] neg_hi:[0,1]
	ds_read_b128 v[120:123], v223 offset:768
	ds_read_b128 v[124:127], v223 offset:784
	s_waitcnt lgkmcnt(8)
	v_pk_fma_f32 v[160:161], v[144:145], v[128:129], v[160:161] op_sel_hi:[0,1,1]
	v_pk_fma_f32 v[168:169], v[146:147], v[128:129], v[168:169] op_sel_hi:[0,1,1]
	v_pk_fma_f32 v[162:163], v[144:145], v[130:131], v[162:163] op_sel_hi:[0,1,1]
	v_pk_fma_f32 v[170:171], v[146:147], v[130:131], v[170:171] op_sel_hi:[0,1,1]
	v_pk_fma_f32 v[164:165], v[144:145], v[132:133], v[164:165] op_sel_hi:[0,1,1]
	v_pk_fma_f32 v[172:173], v[146:147], v[132:133], v[172:173] op_sel_hi:[0,1,1]
	v_pk_fma_f32 v[166:167], v[144:145], v[134:135], v[166:167] op_sel_hi:[0,1,1]
	v_pk_fma_f32 v[174:175], v[146:147], v[134:135], v[174:175] op_sel_hi:[0,1,1]
	ds_read_b128 v[128:131], v222 offset:33536
	ds_read_b128 v[132:135], v222 offset:33552
	ds_read_b32 v144, v226 offset:768
	ds_read_b32 v146, v226 offset:896
	s_waitcnt lgkmcnt(10)
	v_pk_fma_f32 v[184:185], v[184:185], v[104:105], v[160:161]
	v_pk_fma_f32 v[236:237], v[236:237], v[104:105], v[168:169]
	v_pk_fma_f32 v[186:187], v[186:187], v[106:107], v[162:163]
	v_pk_fma_f32 v[248:249], v[248:249], v[106:107], v[170:171]
	v_pk_fma_f32 v[188:189], v[188:189], v[108:109], v[164:165]
	v_pk_fma_f32 v[250:251], v[250:251], v[108:109], v[172:173]
	v_pk_fma_f32 v[190:191], v[190:191], v[110:111], v[166:167]
	v_pk_fma_f32 v[252:253], v[252:253], v[110:111], v[174:175]
	ds_read_b128 v[104:107], v222 offset:17152
	ds_read_b128 v[108:111], v222 offset:17168
	s_waitcnt lgkmcnt(10)
	v_pk_mul_f32 v[156:157], v[184:185], v[136:137]
	v_pk_mul_f32 v[158:159], v[236:237], v[136:137]
	v_pk_fma_f32 v[156:157], v[186:187], v[138:139], v[156:157]
	v_pk_fma_f32 v[158:159], v[248:249], v[138:139], v[158:159]
	v_pk_fma_f32 v[156:157], v[188:189], v[140:141], v[156:157]
	v_pk_fma_f32 v[158:159], v[250:251], v[140:141], v[158:159]
	v_pk_fma_f32 v[156:157], v[190:191], v[142:143], v[156:157]
	v_pk_fma_f32 v[158:159], v[252:253], v[142:143], v[158:159]
	ds_read_b128 v[136:139], v222 offset:768
	ds_read_b128 v[140:143], v222 offset:784
	s_waitcnt lgkmcnt(10)
	v_pk_mul_f32 v[148:149], v[184:185], v[112:113]
	v_pk_mul_f32 v[150:151], v[236:237], v[112:113]
	v_pk_fma_f32 v[148:149], v[186:187], v[114:115], v[148:149]
	v_pk_fma_f32 v[150:151], v[248:249], v[114:115], v[150:151]
	v_pk_fma_f32 v[148:149], v[188:189], v[116:117], v[148:149]
	v_pk_fma_f32 v[150:151], v[250:251], v[116:117], v[150:151]
	v_pk_fma_f32 v[148:149], v[190:191], v[118:119], v[148:149]
	v_pk_fma_f32 v[150:151], v[252:253], v[118:119], v[150:151]
	ds_read_b128 v[112:115], v222 offset:50176
	ds_read_b128 v[116:119], v222 offset:50192
	v_add_f32_e32 v152, v148, v149
	v_add_f32_e32 v153, v156, v157
	v_add_f32_e32 v154, v150, v151
	v_add_f32_e32 v155, v158, v159
	v_add_f32_dpp v152, v152, v152 quad_perm:[1,0,3,2] row_mask:0xf bank_mask:0xf bound_ctrl:1
	v_add_f32_dpp v153, v153, v153 quad_perm:[1,0,3,2] row_mask:0xf bank_mask:0xf bound_ctrl:1
	v_add_f32_dpp v154, v154, v154 quad_perm:[1,0,3,2] row_mask:0xf bank_mask:0xf bound_ctrl:1
	v_add_f32_dpp v155, v155, v155 quad_perm:[1,0,3,2] row_mask:0xf bank_mask:0xf bound_ctrl:1
	v_add_f32_dpp v152, v152, v152 quad_perm:[2,3,0,1] row_mask:0xf bank_mask:0xf bound_ctrl:1
	v_add_f32_dpp v153, v153, v153 quad_perm:[2,3,0,1] row_mask:0xf bank_mask:0xf bound_ctrl:1
	v_add_f32_dpp v154, v154, v154 quad_perm:[2,3,0,1] row_mask:0xf bank_mask:0xf bound_ctrl:1
	v_add_f32_dpp v155, v155, v155 quad_perm:[2,3,0,1] row_mask:0xf bank_mask:0xf bound_ctrl:1
	v_add_f32_dpp v152, v152, v152 row_half_mirror row_mask:0xf bank_mask:0xf bound_ctrl:1
	v_add_f32_dpp v153, v153, v153 row_half_mirror row_mask:0xf bank_mask:0xf bound_ctrl:1
	v_add_f32_dpp v154, v154, v154 row_half_mirror row_mask:0xf bank_mask:0xf bound_ctrl:1
	v_add_f32_dpp v155, v155, v155 row_half_mirror row_mask:0xf bank_mask:0xf bound_ctrl:1
	v_cndmask_b32_e64 v224, v224, v153, s[12:13]
	v_cndmask_b32_e64 v225, v225, v155, s[12:13]
	s_waitcnt lgkmcnt(10)
	v_pk_mul_f32 v[160:161], v[120:121], v[152:153] op_sel_hi:[1,0] neg_lo:[0,1] neg_hi:[0,1]
	v_pk_mul_f32 v[168:169], v[120:121], v[154:155] op_sel_hi:[1,0] neg_lo:[0,1] neg_hi:[0,1]
	v_pk_mul_f32 v[162:163], v[122:123], v[152:153] op_sel_hi:[1,0] neg_lo:[0,1] neg_hi:[0,1]
	v_pk_mul_f32 v[170:171], v[122:123], v[154:155] op_sel_hi:[1,0] neg_lo:[0,1] neg_hi:[0,1]
	v_pk_mul_f32 v[164:165], v[124:125], v[152:153] op_sel_hi:[1,0] neg_lo:[0,1] neg_hi:[0,1]
	v_pk_mul_f32 v[172:173], v[124:125], v[154:155] op_sel_hi:[1,0] neg_lo:[0,1] neg_hi:[0,1]
	v_pk_mul_f32 v[166:167], v[126:127], v[152:153] op_sel_hi:[1,0] neg_lo:[0,1] neg_hi:[0,1]
	v_pk_mul_f32 v[174:175], v[126:127], v[154:155] op_sel_hi:[1,0] neg_lo:[0,1] neg_hi:[0,1]
	ds_read_b128 v[120:123], v223 offset:1024
	ds_read_b128 v[124:127], v223 offset:1040
	s_waitcnt lgkmcnt(8)
	v_pk_fma_f32 v[160:161], v[144:145], v[128:129], v[160:161] op_sel_hi:[0,1,1]
	v_pk_fma_f32 v[168:169], v[146:147], v[128:129], v[168:169] op_sel_hi:[0,1,1]
	v_pk_fma_f32 v[162:163], v[144:145], v[130:131], v[162:163] op_sel_hi:[0,1,1]
	v_pk_fma_f32 v[170:171], v[146:147], v[130:131], v[170:171] op_sel_hi:[0,1,1]
	v_pk_fma_f32 v[164:165], v[144:145], v[132:133], v[164:165] op_sel_hi:[0,1,1]
	v_pk_fma_f32 v[172:173], v[146:147], v[132:133], v[172:173] op_sel_hi:[0,1,1]
	v_pk_fma_f32 v[166:167], v[144:145], v[134:135], v[166:167] op_sel_hi:[0,1,1]
	v_pk_fma_f32 v[174:175], v[146:147], v[134:135], v[174:175] op_sel_hi:[0,1,1]
	ds_read_b128 v[128:131], v222 offset:33792
	ds_read_b128 v[132:135], v222 offset:33808
	ds_read_b32 v144, v226 offset:1024
	ds_read_b32 v146, v226 offset:1152
	s_waitcnt lgkmcnt(10)
	v_pk_fma_f32 v[184:185], v[184:185], v[104:105], v[160:161]
	v_pk_fma_f32 v[236:237], v[236:237], v[104:105], v[168:169]
	v_pk_fma_f32 v[186:187], v[186:187], v[106:107], v[162:163]
	v_pk_fma_f32 v[248:249], v[248:249], v[106:107], v[170:171]
	v_pk_fma_f32 v[188:189], v[188:189], v[108:109], v[164:165]
	v_pk_fma_f32 v[250:251], v[250:251], v[108:109], v[172:173]
	v_pk_fma_f32 v[190:191], v[190:191], v[110:111], v[166:167]
	v_pk_fma_f32 v[252:253], v[252:253], v[110:111], v[174:175]
	ds_read_b128 v[104:107], v222 offset:17408
	ds_read_b128 v[108:111], v222 offset:17424
	s_waitcnt lgkmcnt(10)
	v_pk_mul_f32 v[156:157], v[184:185], v[136:137]
	v_pk_mul_f32 v[158:159], v[236:237], v[136:137]
	v_pk_fma_f32 v[156:157], v[186:187], v[138:139], v[156:157]
	v_pk_fma_f32 v[158:159], v[248:249], v[138:139], v[158:159]
	v_pk_fma_f32 v[156:157], v[188:189], v[140:141], v[156:157]
	v_pk_fma_f32 v[158:159], v[250:251], v[140:141], v[158:159]
	v_pk_fma_f32 v[156:157], v[190:191], v[142:143], v[156:157]
	v_pk_fma_f32 v[158:159], v[252:253], v[142:143], v[158:159]
	ds_read_b128 v[136:139], v222 offset:1024
	ds_read_b128 v[140:143], v222 offset:1040
	s_waitcnt lgkmcnt(10)
	v_pk_mul_f32 v[148:149], v[184:185], v[112:113]
	v_pk_mul_f32 v[150:151], v[236:237], v[112:113]
	v_pk_fma_f32 v[148:149], v[186:187], v[114:115], v[148:149]
	v_pk_fma_f32 v[150:151], v[248:249], v[114:115], v[150:151]
	v_pk_fma_f32 v[148:149], v[188:189], v[116:117], v[148:149]
	v_pk_fma_f32 v[150:151], v[250:251], v[116:117], v[150:151]
	v_pk_fma_f32 v[148:149], v[190:191], v[118:119], v[148:149]
	v_pk_fma_f32 v[150:151], v[252:253], v[118:119], v[150:151]
	ds_read_b128 v[112:115], v222 offset:50432
	ds_read_b128 v[116:119], v222 offset:50448
	v_add_f32_e32 v152, v148, v149
	v_add_f32_e32 v153, v156, v157
	v_add_f32_e32 v154, v150, v151
	v_add_f32_e32 v155, v158, v159
	v_add_f32_dpp v152, v152, v152 quad_perm:[1,0,3,2] row_mask:0xf bank_mask:0xf bound_ctrl:1
	v_add_f32_dpp v153, v153, v153 quad_perm:[1,0,3,2] row_mask:0xf bank_mask:0xf bound_ctrl:1
	v_add_f32_dpp v154, v154, v154 quad_perm:[1,0,3,2] row_mask:0xf bank_mask:0xf bound_ctrl:1
	v_add_f32_dpp v155, v155, v155 quad_perm:[1,0,3,2] row_mask:0xf bank_mask:0xf bound_ctrl:1
	v_add_f32_dpp v152, v152, v152 quad_perm:[2,3,0,1] row_mask:0xf bank_mask:0xf bound_ctrl:1
	v_add_f32_dpp v153, v153, v153 quad_perm:[2,3,0,1] row_mask:0xf bank_mask:0xf bound_ctrl:1
	v_add_f32_dpp v154, v154, v154 quad_perm:[2,3,0,1] row_mask:0xf bank_mask:0xf bound_ctrl:1
	v_add_f32_dpp v155, v155, v155 quad_perm:[2,3,0,1] row_mask:0xf bank_mask:0xf bound_ctrl:1
	v_add_f32_dpp v152, v152, v152 row_half_mirror row_mask:0xf bank_mask:0xf bound_ctrl:1
	v_add_f32_dpp v153, v153, v153 row_half_mirror row_mask:0xf bank_mask:0xf bound_ctrl:1
	v_add_f32_dpp v154, v154, v154 row_half_mirror row_mask:0xf bank_mask:0xf bound_ctrl:1
	v_add_f32_dpp v155, v155, v155 row_half_mirror row_mask:0xf bank_mask:0xf bound_ctrl:1
	v_cndmask_b32_e64 v224, v224, v153, s[14:15]
	v_cndmask_b32_e64 v225, v225, v155, s[14:15]
	s_waitcnt lgkmcnt(10)
	v_pk_mul_f32 v[160:161], v[120:121], v[152:153] op_sel_hi:[1,0] neg_lo:[0,1] neg_hi:[0,1]
	v_pk_mul_f32 v[168:169], v[120:121], v[154:155] op_sel_hi:[1,0] neg_lo:[0,1] neg_hi:[0,1]
	v_pk_mul_f32 v[162:163], v[122:123], v[152:153] op_sel_hi:[1,0] neg_lo:[0,1] neg_hi:[0,1]
	v_pk_mul_f32 v[170:171], v[122:123], v[154:155] op_sel_hi:[1,0] neg_lo:[0,1] neg_hi:[0,1]
	v_pk_mul_f32 v[164:165], v[124:125], v[152:153] op_sel_hi:[1,0] neg_lo:[0,1] neg_hi:[0,1]
	v_pk_mul_f32 v[172:173], v[124:125], v[154:155] op_sel_hi:[1,0] neg_lo:[0,1] neg_hi:[0,1]
	v_pk_mul_f32 v[166:167], v[126:127], v[152:153] op_sel_hi:[1,0] neg_lo:[0,1] neg_hi:[0,1]
	v_pk_mul_f32 v[174:175], v[126:127], v[154:155] op_sel_hi:[1,0] neg_lo:[0,1] neg_hi:[0,1]
	ds_read_b128 v[120:123], v223 offset:1280
	ds_read_b128 v[124:127], v223 offset:1296
	s_waitcnt lgkmcnt(8)
	v_pk_fma_f32 v[160:161], v[144:145], v[128:129], v[160:161] op_sel_hi:[0,1,1]
	v_pk_fma_f32 v[168:169], v[146:147], v[128:129], v[168:169] op_sel_hi:[0,1,1]
	v_pk_fma_f32 v[162:163], v[144:145], v[130:131], v[162:163] op_sel_hi:[0,1,1]
	v_pk_fma_f32 v[170:171], v[146:147], v[130:131], v[170:171] op_sel_hi:[0,1,1]
	v_pk_fma_f32 v[164:165], v[144:145], v[132:133], v[164:165] op_sel_hi:[0,1,1]
	v_pk_fma_f32 v[172:173], v[146:147], v[132:133], v[172:173] op_sel_hi:[0,1,1]
	v_pk_fma_f32 v[166:167], v[144:145], v[134:135], v[166:167] op_sel_hi:[0,1,1]
	v_pk_fma_f32 v[174:175], v[146:147], v[134:135], v[174:175] op_sel_hi:[0,1,1]
	ds_read_b128 v[128:131], v222 offset:34048
	ds_read_b128 v[132:135], v222 offset:34064
	ds_read_b32 v144, v226 offset:1280
	ds_read_b32 v146, v226 offset:1408
	s_waitcnt lgkmcnt(10)
	v_pk_fma_f32 v[184:185], v[184:185], v[104:105], v[160:161]
	v_pk_fma_f32 v[236:237], v[236:237], v[104:105], v[168:169]
	v_pk_fma_f32 v[186:187], v[186:187], v[106:107], v[162:163]
	v_pk_fma_f32 v[248:249], v[248:249], v[106:107], v[170:171]
	v_pk_fma_f32 v[188:189], v[188:189], v[108:109], v[164:165]
	v_pk_fma_f32 v[250:251], v[250:251], v[108:109], v[172:173]
	v_pk_fma_f32 v[190:191], v[190:191], v[110:111], v[166:167]
	v_pk_fma_f32 v[252:253], v[252:253], v[110:111], v[174:175]
	ds_read_b128 v[104:107], v222 offset:17664
	ds_read_b128 v[108:111], v222 offset:17680
	s_waitcnt lgkmcnt(10)
	v_pk_mul_f32 v[156:157], v[184:185], v[136:137]
	v_pk_mul_f32 v[158:159], v[236:237], v[136:137]
	v_pk_fma_f32 v[156:157], v[186:187], v[138:139], v[156:157]
	v_pk_fma_f32 v[158:159], v[248:249], v[138:139], v[158:159]
	v_pk_fma_f32 v[156:157], v[188:189], v[140:141], v[156:157]
	v_pk_fma_f32 v[158:159], v[250:251], v[140:141], v[158:159]
	v_pk_fma_f32 v[156:157], v[190:191], v[142:143], v[156:157]
	v_pk_fma_f32 v[158:159], v[252:253], v[142:143], v[158:159]
	ds_read_b128 v[136:139], v222 offset:1280
	ds_read_b128 v[140:143], v222 offset:1296
	s_waitcnt lgkmcnt(10)
	v_pk_mul_f32 v[148:149], v[184:185], v[112:113]
	v_pk_mul_f32 v[150:151], v[236:237], v[112:113]
	v_pk_fma_f32 v[148:149], v[186:187], v[114:115], v[148:149]
	v_pk_fma_f32 v[150:151], v[248:249], v[114:115], v[150:151]
	v_pk_fma_f32 v[148:149], v[188:189], v[116:117], v[148:149]
	v_pk_fma_f32 v[150:151], v[250:251], v[116:117], v[150:151]
	v_pk_fma_f32 v[148:149], v[190:191], v[118:119], v[148:149]
	v_pk_fma_f32 v[150:151], v[252:253], v[118:119], v[150:151]
	ds_read_b128 v[112:115], v222 offset:50688
	ds_read_b128 v[116:119], v222 offset:50704
	v_add_f32_e32 v152, v148, v149
	v_add_f32_e32 v153, v156, v157
	v_add_f32_e32 v154, v150, v151
	v_add_f32_e32 v155, v158, v159
	v_add_f32_dpp v152, v152, v152 quad_perm:[1,0,3,2] row_mask:0xf bank_mask:0xf bound_ctrl:1
	v_add_f32_dpp v153, v153, v153 quad_perm:[1,0,3,2] row_mask:0xf bank_mask:0xf bound_ctrl:1
	v_add_f32_dpp v154, v154, v154 quad_perm:[1,0,3,2] row_mask:0xf bank_mask:0xf bound_ctrl:1
	v_add_f32_dpp v155, v155, v155 quad_perm:[1,0,3,2] row_mask:0xf bank_mask:0xf bound_ctrl:1
	v_add_f32_dpp v152, v152, v152 quad_perm:[2,3,0,1] row_mask:0xf bank_mask:0xf bound_ctrl:1
	v_add_f32_dpp v153, v153, v153 quad_perm:[2,3,0,1] row_mask:0xf bank_mask:0xf bound_ctrl:1
	v_add_f32_dpp v154, v154, v154 quad_perm:[2,3,0,1] row_mask:0xf bank_mask:0xf bound_ctrl:1
	v_add_f32_dpp v155, v155, v155 quad_perm:[2,3,0,1] row_mask:0xf bank_mask:0xf bound_ctrl:1
	v_add_f32_dpp v152, v152, v152 row_half_mirror row_mask:0xf bank_mask:0xf bound_ctrl:1
	v_add_f32_dpp v153, v153, v153 row_half_mirror row_mask:0xf bank_mask:0xf bound_ctrl:1
	v_add_f32_dpp v154, v154, v154 row_half_mirror row_mask:0xf bank_mask:0xf bound_ctrl:1
	v_add_f32_dpp v155, v155, v155 row_half_mirror row_mask:0xf bank_mask:0xf bound_ctrl:1
	v_cndmask_b32_e64 v224, v224, v153, s[16:17]
	v_cndmask_b32_e64 v225, v225, v155, s[16:17]
	s_waitcnt lgkmcnt(10)
	v_pk_mul_f32 v[160:161], v[120:121], v[152:153] op_sel_hi:[1,0] neg_lo:[0,1] neg_hi:[0,1]
	v_pk_mul_f32 v[168:169], v[120:121], v[154:155] op_sel_hi:[1,0] neg_lo:[0,1] neg_hi:[0,1]
	v_pk_mul_f32 v[162:163], v[122:123], v[152:153] op_sel_hi:[1,0] neg_lo:[0,1] neg_hi:[0,1]
	v_pk_mul_f32 v[170:171], v[122:123], v[154:155] op_sel_hi:[1,0] neg_lo:[0,1] neg_hi:[0,1]
	v_pk_mul_f32 v[164:165], v[124:125], v[152:153] op_sel_hi:[1,0] neg_lo:[0,1] neg_hi:[0,1]
	v_pk_mul_f32 v[172:173], v[124:125], v[154:155] op_sel_hi:[1,0] neg_lo:[0,1] neg_hi:[0,1]
	v_pk_mul_f32 v[166:167], v[126:127], v[152:153] op_sel_hi:[1,0] neg_lo:[0,1] neg_hi:[0,1]
	v_pk_mul_f32 v[174:175], v[126:127], v[154:155] op_sel_hi:[1,0] neg_lo:[0,1] neg_hi:[0,1]
	ds_read_b128 v[120:123], v223 offset:1536
	ds_read_b128 v[124:127], v223 offset:1552
	s_waitcnt lgkmcnt(8)
	v_pk_fma_f32 v[160:161], v[144:145], v[128:129], v[160:161] op_sel_hi:[0,1,1]
	v_pk_fma_f32 v[168:169], v[146:147], v[128:129], v[168:169] op_sel_hi:[0,1,1]
	v_pk_fma_f32 v[162:163], v[144:145], v[130:131], v[162:163] op_sel_hi:[0,1,1]
	v_pk_fma_f32 v[170:171], v[146:147], v[130:131], v[170:171] op_sel_hi:[0,1,1]
	v_pk_fma_f32 v[164:165], v[144:145], v[132:133], v[164:165] op_sel_hi:[0,1,1]
	v_pk_fma_f32 v[172:173], v[146:147], v[132:133], v[172:173] op_sel_hi:[0,1,1]
	v_pk_fma_f32 v[166:167], v[144:145], v[134:135], v[166:167] op_sel_hi:[0,1,1]
	v_pk_fma_f32 v[174:175], v[146:147], v[134:135], v[174:175] op_sel_hi:[0,1,1]
	ds_read_b128 v[128:131], v222 offset:34304
	ds_read_b128 v[132:135], v222 offset:34320
	ds_read_b32 v144, v226 offset:1536
	ds_read_b32 v146, v226 offset:1664
	s_waitcnt lgkmcnt(10)
	v_pk_fma_f32 v[184:185], v[184:185], v[104:105], v[160:161]
	v_pk_fma_f32 v[236:237], v[236:237], v[104:105], v[168:169]
	v_pk_fma_f32 v[186:187], v[186:187], v[106:107], v[162:163]
	v_pk_fma_f32 v[248:249], v[248:249], v[106:107], v[170:171]
	v_pk_fma_f32 v[188:189], v[188:189], v[108:109], v[164:165]
	v_pk_fma_f32 v[250:251], v[250:251], v[108:109], v[172:173]
	v_pk_fma_f32 v[190:191], v[190:191], v[110:111], v[166:167]
	v_pk_fma_f32 v[252:253], v[252:253], v[110:111], v[174:175]
	ds_read_b128 v[104:107], v222 offset:17920
	ds_read_b128 v[108:111], v222 offset:17936
	s_waitcnt lgkmcnt(10)
	v_pk_mul_f32 v[156:157], v[184:185], v[136:137]
	v_pk_mul_f32 v[158:159], v[236:237], v[136:137]
	v_pk_fma_f32 v[156:157], v[186:187], v[138:139], v[156:157]
	v_pk_fma_f32 v[158:159], v[248:249], v[138:139], v[158:159]
	v_pk_fma_f32 v[156:157], v[188:189], v[140:141], v[156:157]
	v_pk_fma_f32 v[158:159], v[250:251], v[140:141], v[158:159]
	v_pk_fma_f32 v[156:157], v[190:191], v[142:143], v[156:157]
	v_pk_fma_f32 v[158:159], v[252:253], v[142:143], v[158:159]
	ds_read_b128 v[136:139], v222 offset:1536
	ds_read_b128 v[140:143], v222 offset:1552
	s_waitcnt lgkmcnt(10)
	v_pk_mul_f32 v[148:149], v[184:185], v[112:113]
	v_pk_mul_f32 v[150:151], v[236:237], v[112:113]
	v_pk_fma_f32 v[148:149], v[186:187], v[114:115], v[148:149]
	v_pk_fma_f32 v[150:151], v[248:249], v[114:115], v[150:151]
	v_pk_fma_f32 v[148:149], v[188:189], v[116:117], v[148:149]
	v_pk_fma_f32 v[150:151], v[250:251], v[116:117], v[150:151]
	v_pk_fma_f32 v[148:149], v[190:191], v[118:119], v[148:149]
	v_pk_fma_f32 v[150:151], v[252:253], v[118:119], v[150:151]
	ds_read_b128 v[112:115], v222 offset:50944
	ds_read_b128 v[116:119], v222 offset:50960
	v_add_f32_e32 v152, v148, v149
	v_add_f32_e32 v153, v156, v157
	v_add_f32_e32 v154, v150, v151
	v_add_f32_e32 v155, v158, v159
	v_add_f32_dpp v152, v152, v152 quad_perm:[1,0,3,2] row_mask:0xf bank_mask:0xf bound_ctrl:1
	v_add_f32_dpp v153, v153, v153 quad_perm:[1,0,3,2] row_mask:0xf bank_mask:0xf bound_ctrl:1
	v_add_f32_dpp v154, v154, v154 quad_perm:[1,0,3,2] row_mask:0xf bank_mask:0xf bound_ctrl:1
	v_add_f32_dpp v155, v155, v155 quad_perm:[1,0,3,2] row_mask:0xf bank_mask:0xf bound_ctrl:1
	v_add_f32_dpp v152, v152, v152 quad_perm:[2,3,0,1] row_mask:0xf bank_mask:0xf bound_ctrl:1
	v_add_f32_dpp v153, v153, v153 quad_perm:[2,3,0,1] row_mask:0xf bank_mask:0xf bound_ctrl:1
	v_add_f32_dpp v154, v154, v154 quad_perm:[2,3,0,1] row_mask:0xf bank_mask:0xf bound_ctrl:1
	v_add_f32_dpp v155, v155, v155 quad_perm:[2,3,0,1] row_mask:0xf bank_mask:0xf bound_ctrl:1
	v_add_f32_dpp v152, v152, v152 row_half_mirror row_mask:0xf bank_mask:0xf bound_ctrl:1
	v_add_f32_dpp v153, v153, v153 row_half_mirror row_mask:0xf bank_mask:0xf bound_ctrl:1
	v_add_f32_dpp v154, v154, v154 row_half_mirror row_mask:0xf bank_mask:0xf bound_ctrl:1
	v_add_f32_dpp v155, v155, v155 row_half_mirror row_mask:0xf bank_mask:0xf bound_ctrl:1
	v_cndmask_b32_e64 v224, v224, v153, s[18:19]
	v_cndmask_b32_e64 v225, v225, v155, s[18:19]
	s_waitcnt lgkmcnt(10)
	v_pk_mul_f32 v[160:161], v[120:121], v[152:153] op_sel_hi:[1,0] neg_lo:[0,1] neg_hi:[0,1]
	v_pk_mul_f32 v[168:169], v[120:121], v[154:155] op_sel_hi:[1,0] neg_lo:[0,1] neg_hi:[0,1]
	v_pk_mul_f32 v[162:163], v[122:123], v[152:153] op_sel_hi:[1,0] neg_lo:[0,1] neg_hi:[0,1]
	v_pk_mul_f32 v[170:171], v[122:123], v[154:155] op_sel_hi:[1,0] neg_lo:[0,1] neg_hi:[0,1]
	v_pk_mul_f32 v[164:165], v[124:125], v[152:153] op_sel_hi:[1,0] neg_lo:[0,1] neg_hi:[0,1]
	v_pk_mul_f32 v[172:173], v[124:125], v[154:155] op_sel_hi:[1,0] neg_lo:[0,1] neg_hi:[0,1]
	v_pk_mul_f32 v[166:167], v[126:127], v[152:153] op_sel_hi:[1,0] neg_lo:[0,1] neg_hi:[0,1]
	v_pk_mul_f32 v[174:175], v[126:127], v[154:155] op_sel_hi:[1,0] neg_lo:[0,1] neg_hi:[0,1]
	ds_read_b128 v[120:123], v223 offset:1792
	ds_read_b128 v[124:127], v223 offset:1808
	s_waitcnt lgkmcnt(8)
	v_pk_fma_f32 v[160:161], v[144:145], v[128:129], v[160:161] op_sel_hi:[0,1,1]
	v_pk_fma_f32 v[168:169], v[146:147], v[128:129], v[168:169] op_sel_hi:[0,1,1]
	v_pk_fma_f32 v[162:163], v[144:145], v[130:131], v[162:163] op_sel_hi:[0,1,1]
	v_pk_fma_f32 v[170:171], v[146:147], v[130:131], v[170:171] op_sel_hi:[0,1,1]
	v_pk_fma_f32 v[164:165], v[144:145], v[132:133], v[164:165] op_sel_hi:[0,1,1]
	v_pk_fma_f32 v[172:173], v[146:147], v[132:133], v[172:173] op_sel_hi:[0,1,1]
	v_pk_fma_f32 v[166:167], v[144:145], v[134:135], v[166:167] op_sel_hi:[0,1,1]
	v_pk_fma_f32 v[174:175], v[146:147], v[134:135], v[174:175] op_sel_hi:[0,1,1]
	ds_read_b128 v[128:131], v222 offset:34560
	ds_read_b128 v[132:135], v222 offset:34576
	ds_read_b32 v144, v226 offset:1792
	ds_read_b32 v146, v226 offset:1920
	s_waitcnt lgkmcnt(10)
	v_pk_fma_f32 v[184:185], v[184:185], v[104:105], v[160:161]
	v_pk_fma_f32 v[236:237], v[236:237], v[104:105], v[168:169]
	v_pk_fma_f32 v[186:187], v[186:187], v[106:107], v[162:163]
	v_pk_fma_f32 v[248:249], v[248:249], v[106:107], v[170:171]
	v_pk_fma_f32 v[188:189], v[188:189], v[108:109], v[164:165]
	v_pk_fma_f32 v[250:251], v[250:251], v[108:109], v[172:173]
	v_pk_fma_f32 v[190:191], v[190:191], v[110:111], v[166:167]
	v_pk_fma_f32 v[252:253], v[252:253], v[110:111], v[174:175]
	ds_read_b128 v[104:107], v222 offset:18176
	ds_read_b128 v[108:111], v222 offset:18192
	s_waitcnt lgkmcnt(10)
	v_pk_mul_f32 v[156:157], v[184:185], v[136:137]
	v_pk_mul_f32 v[158:159], v[236:237], v[136:137]
	v_pk_fma_f32 v[156:157], v[186:187], v[138:139], v[156:157]
	v_pk_fma_f32 v[158:159], v[248:249], v[138:139], v[158:159]
	v_pk_fma_f32 v[156:157], v[188:189], v[140:141], v[156:157]
	v_pk_fma_f32 v[158:159], v[250:251], v[140:141], v[158:159]
	v_pk_fma_f32 v[156:157], v[190:191], v[142:143], v[156:157]
	v_pk_fma_f32 v[158:159], v[252:253], v[142:143], v[158:159]
	ds_read_b128 v[136:139], v222 offset:1792
	ds_read_b128 v[140:143], v222 offset:1808
	s_waitcnt lgkmcnt(10)
	v_pk_mul_f32 v[148:149], v[184:185], v[112:113]
	v_pk_mul_f32 v[150:151], v[236:237], v[112:113]
	v_pk_fma_f32 v[148:149], v[186:187], v[114:115], v[148:149]
	v_pk_fma_f32 v[150:151], v[248:249], v[114:115], v[150:151]
	v_pk_fma_f32 v[148:149], v[188:189], v[116:117], v[148:149]
	v_pk_fma_f32 v[150:151], v[250:251], v[116:117], v[150:151]
	v_pk_fma_f32 v[148:149], v[190:191], v[118:119], v[148:149]
	v_pk_fma_f32 v[150:151], v[252:253], v[118:119], v[150:151]
	ds_read_b128 v[112:115], v222 offset:51200
	ds_read_b128 v[116:119], v222 offset:51216
	v_add_f32_e32 v152, v148, v149
	v_add_f32_e32 v153, v156, v157
	v_add_f32_e32 v154, v150, v151
	v_add_f32_e32 v155, v158, v159
	v_add_f32_dpp v152, v152, v152 quad_perm:[1,0,3,2] row_mask:0xf bank_mask:0xf bound_ctrl:1
	v_add_f32_dpp v153, v153, v153 quad_perm:[1,0,3,2] row_mask:0xf bank_mask:0xf bound_ctrl:1
	v_add_f32_dpp v154, v154, v154 quad_perm:[1,0,3,2] row_mask:0xf bank_mask:0xf bound_ctrl:1
	v_add_f32_dpp v155, v155, v155 quad_perm:[1,0,3,2] row_mask:0xf bank_mask:0xf bound_ctrl:1
	v_add_f32_dpp v152, v152, v152 quad_perm:[2,3,0,1] row_mask:0xf bank_mask:0xf bound_ctrl:1
	v_add_f32_dpp v153, v153, v153 quad_perm:[2,3,0,1] row_mask:0xf bank_mask:0xf bound_ctrl:1
	v_add_f32_dpp v154, v154, v154 quad_perm:[2,3,0,1] row_mask:0xf bank_mask:0xf bound_ctrl:1
	v_add_f32_dpp v155, v155, v155 quad_perm:[2,3,0,1] row_mask:0xf bank_mask:0xf bound_ctrl:1
	v_add_f32_dpp v152, v152, v152 row_half_mirror row_mask:0xf bank_mask:0xf bound_ctrl:1
	v_add_f32_dpp v153, v153, v153 row_half_mirror row_mask:0xf bank_mask:0xf bound_ctrl:1
	v_add_f32_dpp v154, v154, v154 row_half_mirror row_mask:0xf bank_mask:0xf bound_ctrl:1
	v_add_f32_dpp v155, v155, v155 row_half_mirror row_mask:0xf bank_mask:0xf bound_ctrl:1
	v_cndmask_b32_e64 v224, v224, v153, s[20:21]
	v_cndmask_b32_e64 v225, v225, v155, s[20:21]
	s_waitcnt lgkmcnt(10)
	v_pk_mul_f32 v[160:161], v[120:121], v[152:153] op_sel_hi:[1,0] neg_lo:[0,1] neg_hi:[0,1]
	v_pk_mul_f32 v[168:169], v[120:121], v[154:155] op_sel_hi:[1,0] neg_lo:[0,1] neg_hi:[0,1]
	v_pk_mul_f32 v[162:163], v[122:123], v[152:153] op_sel_hi:[1,0] neg_lo:[0,1] neg_hi:[0,1]
	v_pk_mul_f32 v[170:171], v[122:123], v[154:155] op_sel_hi:[1,0] neg_lo:[0,1] neg_hi:[0,1]
	v_pk_mul_f32 v[164:165], v[124:125], v[152:153] op_sel_hi:[1,0] neg_lo:[0,1] neg_hi:[0,1]
	v_pk_mul_f32 v[172:173], v[124:125], v[154:155] op_sel_hi:[1,0] neg_lo:[0,1] neg_hi:[0,1]
	v_pk_mul_f32 v[166:167], v[126:127], v[152:153] op_sel_hi:[1,0] neg_lo:[0,1] neg_hi:[0,1]
	v_pk_mul_f32 v[174:175], v[126:127], v[154:155] op_sel_hi:[1,0] neg_lo:[0,1] neg_hi:[0,1]
	ds_read_b128 v[120:123], v223 offset:2048
	ds_read_b128 v[124:127], v223 offset:2064
	s_waitcnt lgkmcnt(8)
	v_pk_fma_f32 v[160:161], v[144:145], v[128:129], v[160:161] op_sel_hi:[0,1,1]
	v_pk_fma_f32 v[168:169], v[146:147], v[128:129], v[168:169] op_sel_hi:[0,1,1]
	v_pk_fma_f32 v[162:163], v[144:145], v[130:131], v[162:163] op_sel_hi:[0,1,1]
	v_pk_fma_f32 v[170:171], v[146:147], v[130:131], v[170:171] op_sel_hi:[0,1,1]
	v_pk_fma_f32 v[164:165], v[144:145], v[132:133], v[164:165] op_sel_hi:[0,1,1]
	v_pk_fma_f32 v[172:173], v[146:147], v[132:133], v[172:173] op_sel_hi:[0,1,1]
	v_pk_fma_f32 v[166:167], v[144:145], v[134:135], v[166:167] op_sel_hi:[0,1,1]
	v_pk_fma_f32 v[174:175], v[146:147], v[134:135], v[174:175] op_sel_hi:[0,1,1]
	ds_read_b128 v[128:131], v222 offset:34816
	ds_read_b128 v[132:135], v222 offset:34832
	ds_read_b32 v144, v226 offset:2048
	ds_read_b32 v146, v226 offset:2176
	s_waitcnt lgkmcnt(10)
	v_pk_fma_f32 v[184:185], v[184:185], v[104:105], v[160:161]
	v_pk_fma_f32 v[236:237], v[236:237], v[104:105], v[168:169]
	v_pk_fma_f32 v[186:187], v[186:187], v[106:107], v[162:163]
	v_pk_fma_f32 v[248:249], v[248:249], v[106:107], v[170:171]
	v_pk_fma_f32 v[188:189], v[188:189], v[108:109], v[164:165]
	v_pk_fma_f32 v[250:251], v[250:251], v[108:109], v[172:173]
	v_pk_fma_f32 v[190:191], v[190:191], v[110:111], v[166:167]
	v_pk_fma_f32 v[252:253], v[252:253], v[110:111], v[174:175]
	ds_read_b128 v[104:107], v222 offset:18432
	ds_read_b128 v[108:111], v222 offset:18448
	s_waitcnt lgkmcnt(10)
	v_pk_mul_f32 v[156:157], v[184:185], v[136:137]
	v_pk_mul_f32 v[158:159], v[236:237], v[136:137]
	v_pk_fma_f32 v[156:157], v[186:187], v[138:139], v[156:157]
	v_pk_fma_f32 v[158:159], v[248:249], v[138:139], v[158:159]
	v_pk_fma_f32 v[156:157], v[188:189], v[140:141], v[156:157]
	v_pk_fma_f32 v[158:159], v[250:251], v[140:141], v[158:159]
	v_pk_fma_f32 v[156:157], v[190:191], v[142:143], v[156:157]
	v_pk_fma_f32 v[158:159], v[252:253], v[142:143], v[158:159]
	ds_read_b128 v[136:139], v222 offset:2048
	ds_read_b128 v[140:143], v222 offset:2064
	s_addk_i32 s27, 0x800
	v_add_u32_e32 v222, s27, v177
	v_add_u32_e32 v223, s27, v197
	v_add_u32_e32 v226, s27, v216
	s_cmpk_lg_u32 s27, 0x4000
	s_cbranch_scc1 .Lrwkv_scan_loop
	v_add_f32_e32 v153, v156, v157
	v_add_f32_e32 v155, v158, v159
	s_nop 1
	v_add_f32_dpp v153, v153, v153 quad_perm:[1,0,3,2] row_mask:0xf bank_mask:0xf bound_ctrl:1
	v_add_f32_dpp v155, v155, v155 quad_perm:[1,0,3,2] row_mask:0xf bank_mask:0xf bound_ctrl:1
	s_nop 1
	v_add_f32_dpp v153, v153, v153 quad_perm:[2,3,0,1] row_mask:0xf bank_mask:0xf bound_ctrl:1
	v_add_f32_dpp v155, v155, v155 quad_perm:[2,3,0,1] row_mask:0xf bank_mask:0xf bound_ctrl:1
	s_nop 1
	v_add_f32_dpp v153, v153, v153 row_half_mirror row_mask:0xf bank_mask:0xf bound_ctrl:1
	v_add_f32_dpp v155, v155, v155 row_half_mirror row_mask:0xf bank_mask:0xf bound_ctrl:1
	v_cndmask_b32_e64 v224, v224, v153, s[8:9]
	v_cndmask_b32_e64 v225, v225, v155, s[8:9]
	ds_write_b32 v227, v224
	ds_write_b32 v227, v225 offset:128
	s_waitcnt lgkmcnt(0)
	s_branch .LBB0_263

.LBB0_283:
	v_mfma_f32_16x16x32_bf16 v[130:133], v[40:43], v[0:3], 0
	v_add_u32_e32 v73, 0x400, v97
	v_add_u32_e32 v138, 0x50, v63
	v_add_u32_e32 v139, 0x58, v63
	v_mfma_f32_16x16x32_bf16 v[134:137], v[40:43], v[8:11], 0
	s_nop 7
	ds_write2_b32 v97, v130, v134 offset1:16
	ds_write2_b32 v97, v131, v135 offset0:130 offset1:146
	ds_write2_b32 v73, v132, v136 offset0:4 offset1:20
	ds_write2_b32 v73, v133, v137 offset0:134 offset1:150
	v_mfma_f32_16x16x32_bf16 v[130:133], v[40:43], v[16:19], 0
	v_add_u32_e32 v140, 0x60, v63
	v_add_u32_e32 v141, 0x68, v63
	v_add_u32_e32 v142, 0x70, v63
	v_mfma_f32_16x16x32_bf16 v[134:137], v[40:43], v[24:27], 0
	s_nop 7
	ds_write2_b32 v97, v130, v134 offset0:32 offset1:48
	ds_write2_b32 v97, v131, v135 offset0:162 offset1:178
	ds_write2_b32 v73, v132, v136 offset0:36 offset1:52
	ds_write2_b32 v73, v133, v137 offset0:166 offset1:182
	v_mfma_f32_16x16x32_bf16 v[130:133], v[40:43], v[4:7], 0
	v_add_u32_e32 v143, 0x78, v63
	s_add_u32 s18, s18, 0x28000
	s_addc_u32 s19, s19, 0
	v_mfma_f32_16x16x32_bf16 v[134:137], v[40:43], v[12:15], 0
	s_nop 7
	ds_write2_b32 v97, v130, v134 offset0:64 offset1:80
	ds_write2_b32 v97, v131, v135 offset0:194 offset1:210
	ds_write2_b32 v73, v132, v136 offset0:68 offset1:84
	ds_write2_b32 v73, v133, v137 offset0:198 offset1:214
	v_mfma_f32_16x16x32_bf16 v[130:133], v[40:43], v[20:23], 0
	v_add_u32_e32 v134, 48, v63
	v_add_u32_e32 v135, 56, v63
	v_add_u32_e32 v136, 64, v63
	v_mfma_f32_16x16x32_bf16 v[40:43], v[40:43], v[28:31], 0
	s_nop 7
	ds_write2_b32 v97, v130, v40 offset0:96 offset1:112
	ds_write2_b32 v97, v131, v41 offset0:226 offset1:242
	ds_write2_b32 v73, v132, v42 offset0:100 offset1:116
	ds_write2_b32 v73, v133, v43 offset0:230 offset1:246
	s_waitcnt lgkmcnt(0)
	v_add_u32_e32 v130, 16, v63
	v_add_u32_e32 v131, 24, v63
	v_add_u32_e32 v132, 32, v63
	v_add_u32_e32 v133, 40, v63
	v_add_u32_e32 v137, 72, v63
	ds_read2st64_b32 v[164:165], v63 offset1:1
	ds_read2_b32 v[166:167], v63 offset0:130 offset1:194
	ds_read2st64_b32 v[168:169], v130 offset0:4 offset1:5
	ds_read2st64_b32 v[170:171], v131 offset0:6 offset1:7
	ds_read2st64_b32 v[172:173], v132 offset0:8 offset1:9
	ds_read2st64_b32 v[174:175], v133 offset0:10 offset1:11
	ds_read2st64_b32 v[176:177], v134 offset0:12 offset1:13
	ds_read2st64_b32 v[178:179], v135 offset0:14 offset1:15
	ds_read2st64_b32 v[180:181], v136 offset0:16 offset1:17
	ds_read2st64_b32 v[182:183], v137 offset0:18 offset1:19
	ds_read2st64_b32 v[184:185], v138 offset0:20 offset1:21
	ds_read2st64_b32 v[186:187], v139 offset0:22 offset1:23
	ds_read2st64_b32 v[188:189], v140 offset0:24 offset1:25
	ds_read2st64_b32 v[190:191], v141 offset0:26 offset1:27
	ds_read2st64_b32 v[192:193], v142 offset0:28 offset1:29
	s_waitcnt lgkmcnt(14)
	v_pk_fma_f32 v[40:41], v[80:81], v[76:77], v[164:165]
	ds_read2st64_b32 v[194:195], v143 offset0:30 offset1:31
	v_xor_b32_e32 v42, 0x80000000, v77
	v_mov_b32_e32 v43, v76
	v_pk_fma_f32 v[76:77], v[82:83], v[42:43], v[40:41]
	s_waitcnt lgkmcnt(14)
	v_pk_fma_f32 v[40:41], v[80:81], v[76:77], v[166:167]
	v_xor_b32_e32 v42, 0x80000000, v77
	v_mov_b32_e32 v43, v76
	v_pk_fma_f32 v[76:77], v[82:83], v[42:43], v[40:41]
	s_waitcnt lgkmcnt(13)
	v_pk_fma_f32 v[40:41], v[80:81], v[76:77], v[168:169]
	v_xor_b32_e32 v42, 0x80000000, v77
	v_mov_b32_e32 v43, v76
	v_pk_fma_f32 v[76:77], v[82:83], v[42:43], v[40:41]
	s_waitcnt lgkmcnt(12)
	v_pk_fma_f32 v[40:41], v[80:81], v[76:77], v[170:171]
	v_xor_b32_e32 v42, 0x80000000, v77
	v_mov_b32_e32 v43, v76
	v_pk_fma_f32 v[76:77], v[82:83], v[42:43], v[40:41]
	s_waitcnt lgkmcnt(11)
	v_pk_fma_f32 v[40:41], v[80:81], v[76:77], v[172:173]
	v_xor_b32_e32 v42, 0x80000000, v77
	v_mov_b32_e32 v43, v76
	v_pk_fma_f32 v[76:77], v[82:83], v[42:43], v[40:41]
	s_waitcnt lgkmcnt(10)
	v_pk_fma_f32 v[40:41], v[80:81], v[76:77], v[174:175]
	v_xor_b32_e32 v42, 0x80000000, v77
	v_mov_b32_e32 v43, v76
	v_pk_fma_f32 v[76:77], v[82:83], v[42:43], v[40:41]
	s_waitcnt lgkmcnt(9)
	v_pk_fma_f32 v[40:41], v[80:81], v[76:77], v[176:177]
	v_xor_b32_e32 v42, 0x80000000, v77
	v_mov_b32_e32 v43, v76
	v_pk_fma_f32 v[76:77], v[82:83], v[42:43], v[40:41]
	s_waitcnt lgkmcnt(8)
	v_pk_fma_f32 v[40:41], v[80:81], v[76:77], v[178:179]
	v_xor_b32_e32 v42, 0x80000000, v77
	v_mov_b32_e32 v43, v76
	v_pk_fma_f32 v[76:77], v[82:83], v[42:43], v[40:41]
	s_waitcnt lgkmcnt(7)
	v_pk_fma_f32 v[40:41], v[80:81], v[76:77], v[180:181]
	v_xor_b32_e32 v42, 0x80000000, v77
	v_mov_b32_e32 v43, v76
	v_pk_fma_f32 v[76:77], v[82:83], v[42:43], v[40:41]
	s_waitcnt lgkmcnt(6)
	v_pk_fma_f32 v[40:41], v[80:81], v[76:77], v[182:183]
	v_xor_b32_e32 v42, 0x80000000, v77
	v_mov_b32_e32 v43, v76
	v_pk_fma_f32 v[76:77], v[82:83], v[42:43], v[40:41]
	s_waitcnt lgkmcnt(5)
	v_pk_fma_f32 v[40:41], v[80:81], v[76:77], v[184:185]
	v_xor_b32_e32 v42, 0x80000000, v77
	v_mov_b32_e32 v43, v76
	v_pk_fma_f32 v[76:77], v[82:83], v[42:43], v[40:41]
	s_waitcnt lgkmcnt(4)
	v_pk_fma_f32 v[40:41], v[80:81], v[76:77], v[186:187]
	v_xor_b32_e32 v42, 0x80000000, v77
	v_mov_b32_e32 v43, v76
	v_pk_fma_f32 v[76:77], v[82:83], v[42:43], v[40:41]
	s_waitcnt lgkmcnt(3)
	v_pk_fma_f32 v[40:41], v[80:81], v[76:77], v[188:189]
	v_xor_b32_e32 v42, 0x80000000, v77
	v_mov_b32_e32 v43, v76
	v_pk_fma_f32 v[76:77], v[82:83], v[42:43], v[40:41]
	s_waitcnt lgkmcnt(2)
	v_pk_fma_f32 v[40:41], v[80:81], v[76:77], v[190:191]
	v_xor_b32_e32 v42, 0x80000000, v77
	v_mov_b32_e32 v43, v76
	v_pk_fma_f32 v[76:77], v[82:83], v[42:43], v[40:41]
	s_waitcnt lgkmcnt(1)
	v_pk_fma_f32 v[40:41], v[80:81], v[76:77], v[192:193]
	v_xor_b32_e32 v42, 0x80000000, v77
	v_mov_b32_e32 v43, v76
	v_pk_fma_f32 v[76:77], v[82:83], v[42:43], v[40:41]
	s_waitcnt lgkmcnt(0)
	v_pk_fma_f32 v[40:41], v[80:81], v[76:77], v[194:195]
	v_xor_b32_e32 v42, 0x80000000, v77
	v_mov_b32_e32 v43, v76
	v_pk_fma_f32 v[76:77], v[82:83], v[42:43], v[40:41]
	s_cmp_eq_u32 s18, 0x280000
	s_waitcnt vmcnt(0)
	v_mov_b64_e32 v[42:43], v[38:39]
	v_mov_b64_e32 v[40:41], v[36:37]
	s_cbranch_scc1 .LBB0_286

.LBB0_291:
	v_mfma_f32_16x16x32_bf16 v[144:147], v[40:43], v[0:3], 0
	s_mov_b32 s0, 0xbf3a00e3
	s_add_u32 s18, s18, 0x28000
	s_addc_u32 s19, s19, 0
	v_mfma_f32_16x16x32_bf16 v[148:151], v[40:43], v[8:11], 0
	s_nop 7
	ds_write2_b32 v97, v144, v148 offset1:16
	ds_write2_b32 v97, v145, v149 offset0:130 offset1:146
	ds_write2_b32 v73, v146, v150 offset0:4 offset1:20
	v_mfma_f32_16x16x32_bf16 v[152:155], v[40:43], v[16:19], 0
	s_cmp_eq_u32 s18, 0x280000
	v_mfma_f32_16x16x32_bf16 v[156:159], v[40:43], v[24:27], 0
	ds_write2_b32 v73, v147, v151 offset0:134 offset1:150
	s_nop 6
	ds_write2_b32 v97, v152, v156 offset0:32 offset1:48
	ds_write2_b32 v97, v153, v157 offset0:162 offset1:178
	v_mfma_f32_16x16x32_bf16 v[160:163], v[40:43], v[4:7], 0
	v_mfma_f32_16x16x32_bf16 v[144:147], v[40:43], v[12:15], 0
	ds_write2_b32 v73, v154, v158 offset0:36 offset1:52
	ds_write2_b32 v73, v155, v159 offset0:166 offset1:182
	s_nop 5
	ds_write2_b32 v97, v160, v144 offset0:64 offset1:80
	ds_write2_b32 v97, v161, v145 offset0:194 offset1:210
	ds_write2_b32 v73, v162, v146 offset0:68 offset1:84
	ds_write2_b32 v73, v163, v147 offset0:198 offset1:214
	v_mfma_f32_16x16x32_bf16 v[148:151], v[40:43], v[20:23], 0
	v_xor_b32_e32 v144, 0x80000000, v95
	v_mov_b32_e32 v145, v94
	v_mfma_f32_16x16x32_bf16 v[40:43], v[40:43], v[28:31], 0
	s_nop 7
	ds_write2_b32 v97, v148, v40 offset0:96 offset1:112
	ds_write2_b32 v97, v149, v41 offset0:226 offset1:242
	ds_write2_b32 v73, v150, v42 offset0:100 offset1:116
	ds_write2_b32 v73, v151, v43 offset0:230 offset1:246
	s_waitcnt lgkmcnt(0)
	ds_read2st64_b32 v[164:165], v63 offset1:1
	ds_read2_b32 v[166:167], v63 offset0:130 offset1:194
	ds_read2st64_b32 v[168:169], v130 offset0:4 offset1:5
	ds_read2st64_b32 v[170:171], v131 offset0:6 offset1:7
	ds_read2st64_b32 v[172:173], v132 offset0:8 offset1:9
	ds_read2st64_b32 v[174:175], v133 offset0:10 offset1:11
	ds_read2st64_b32 v[176:177], v134 offset0:12 offset1:13
	ds_read2st64_b32 v[178:179], v135 offset0:14 offset1:15
	ds_read2st64_b32 v[180:181], v136 offset0:16 offset1:17
	ds_read2st64_b32 v[182:183], v137 offset0:18 offset1:19
	ds_read2st64_b32 v[184:185], v138 offset0:20 offset1:21
	ds_read2st64_b32 v[186:187], v139 offset0:22 offset1:23
	ds_read2st64_b32 v[188:189], v140 offset0:24 offset1:25
	ds_read2st64_b32 v[190:191], v141 offset0:26 offset1:27
	ds_read2st64_b32 v[192:193], v142 offset0:28 offset1:29
	s_waitcnt lgkmcnt(14)
	v_pk_fma_f32 v[42:43], v[80:81], v[94:95], v[164:165]
	ds_read2st64_b32 v[194:195], v143 offset0:30 offset1:31
	s_nop 0
	v_pk_fma_f32 v[164:165], v[82:83], v[144:145], v[42:43]
	s_waitcnt lgkmcnt(14)
	v_pk_fma_f32 v[42:43], v[80:81], v[164:165], v[166:167]
	v_xor_b32_e32 v144, 0x80000000, v165
	v_mov_b32_e32 v145, v164
	v_pk_fma_f32 v[166:167], v[82:83], v[144:145], v[42:43]
	s_waitcnt lgkmcnt(13)
	v_pk_fma_f32 v[42:43], v[80:81], v[166:167], v[168:169]
	v_xor_b32_e32 v144, 0x80000000, v167
	v_mov_b32_e32 v145, v166
	v_pk_fma_f32 v[168:169], v[82:83], v[144:145], v[42:43]
	s_waitcnt lgkmcnt(12)
	v_pk_fma_f32 v[42:43], v[80:81], v[168:169], v[170:171]
	v_xor_b32_e32 v144, 0x80000000, v169
	v_mov_b32_e32 v145, v168
	v_pk_fma_f32 v[170:171], v[82:83], v[144:145], v[42:43]
	s_waitcnt lgkmcnt(11)
	v_pk_fma_f32 v[42:43], v[80:81], v[170:171], v[172:173]
	v_xor_b32_e32 v144, 0x80000000, v171
	v_mov_b32_e32 v145, v170
	v_pk_fma_f32 v[172:173], v[82:83], v[144:145], v[42:43]
	s_waitcnt lgkmcnt(10)
	v_pk_fma_f32 v[42:43], v[80:81], v[172:173], v[174:175]
	v_xor_b32_e32 v144, 0x80000000, v173
	v_mov_b32_e32 v145, v172
	v_pk_fma_f32 v[174:175], v[82:83], v[144:145], v[42:43]
	s_waitcnt lgkmcnt(9)
	v_pk_fma_f32 v[42:43], v[80:81], v[174:175], v[176:177]
	v_xor_b32_e32 v144, 0x80000000, v175
	v_mov_b32_e32 v145, v174
	v_pk_fma_f32 v[176:177], v[82:83], v[144:145], v[42:43]
	s_waitcnt lgkmcnt(8)
	v_pk_fma_f32 v[42:43], v[80:81], v[176:177], v[178:179]
	v_xor_b32_e32 v144, 0x80000000, v177
	v_mov_b32_e32 v145, v176
	v_pk_fma_f32 v[178:179], v[82:83], v[144:145], v[42:43]
	s_waitcnt lgkmcnt(7)
	v_pk_fma_f32 v[42:43], v[80:81], v[178:179], v[180:181]
	v_xor_b32_e32 v144, 0x80000000, v179
	v_mov_b32_e32 v145, v178
	v_pk_fma_f32 v[180:181], v[82:83], v[144:145], v[42:43]
	s_waitcnt lgkmcnt(6)
	v_pk_fma_f32 v[42:43], v[80:81], v[180:181], v[182:183]
	v_xor_b32_e32 v144, 0x80000000, v181
	v_mov_b32_e32 v145, v180
	v_pk_fma_f32 v[182:183], v[82:83], v[144:145], v[42:43]
	s_waitcnt lgkmcnt(5)
	v_pk_fma_f32 v[42:43], v[80:81], v[182:183], v[184:185]
	v_xor_b32_e32 v144, 0x80000000, v183
	v_mov_b32_e32 v145, v182
	v_pk_fma_f32 v[184:185], v[82:83], v[144:145], v[42:43]
	s_waitcnt lgkmcnt(4)
	v_pk_fma_f32 v[42:43], v[80:81], v[184:185], v[186:187]
	v_xor_b32_e32 v144, 0x80000000, v185
	v_mov_b32_e32 v145, v184
	v_pk_fma_f32 v[186:187], v[82:83], v[144:145], v[42:43]
	s_waitcnt lgkmcnt(3)
	v_pk_fma_f32 v[42:43], v[80:81], v[186:187], v[188:189]
	v_xor_b32_e32 v144, 0x80000000, v187
	v_mov_b32_e32 v145, v186
	v_pk_fma_f32 v[188:189], v[82:83], v[144:145], v[42:43]
	s_waitcnt lgkmcnt(2)
	v_pk_fma_f32 v[42:43], v[80:81], v[188:189], v[190:191]
	v_xor_b32_e32 v144, 0x80000000, v189
	v_mov_b32_e32 v145, v188
	v_pk_fma_f32 v[190:191], v[82:83], v[144:145], v[42:43]
	s_waitcnt lgkmcnt(1)
	v_pk_fma_f32 v[42:43], v[80:81], v[190:191], v[192:193]
	v_xor_b32_e32 v144, 0x80000000, v191
	v_mov_b32_e32 v145, v190
	v_pk_fma_f32 v[192:193], v[82:83], v[144:145], v[42:43]
	s_waitcnt lgkmcnt(0)
	v_pk_fma_f32 v[42:43], v[80:81], v[192:193], v[194:195]
	v_xor_b32_e32 v144, 0x80000000, v193
	v_mov_b32_e32 v145, v192
	v_pk_fma_f32 v[94:95], v[82:83], v[144:145], v[42:43]
	ds_write2st64_b32 v63, v164, v165 offset1:1
	ds_write2_b32 v63, v166, v167 offset0:130 offset1:194
	ds_write2st64_b32 v130, v168, v169 offset0:4 offset1:5
	ds_write2st64_b32 v131, v170, v171 offset0:6 offset1:7
	ds_write2st64_b32 v132, v172, v173 offset0:8 offset1:9
	ds_write2st64_b32 v133, v174, v175 offset0:10 offset1:11
	ds_write2st64_b32 v134, v176, v177 offset0:12 offset1:13
	ds_write2st64_b32 v135, v178, v179 offset0:14 offset1:15
	ds_write2st64_b32 v136, v180, v181 offset0:16 offset1:17
	ds_write2st64_b32 v137, v182, v183 offset0:18 offset1:19
	ds_write2st64_b32 v138, v184, v185 offset0:20 offset1:21
	ds_write2st64_b32 v139, v186, v187 offset0:22 offset1:23
	ds_write2st64_b32 v140, v188, v189 offset0:24 offset1:25
	ds_write2st64_b32 v141, v190, v191 offset0:26 offset1:27
	ds_write2st64_b32 v142, v192, v193 offset0:28 offset1:29
	ds_write2st64_b32 v143, v94, v95 offset0:30 offset1:31
	s_waitcnt lgkmcnt(0)
	ds_read2_b32 v[164:165], v96 offset0:0 offset1:4
	ds_read2_b32 v[166:167], v96 offset0:8 offset1:12
	ds_read2_b32 v[168:169], v96 offset0:16 offset1:20
	ds_read2_b32 v[170:171], v96 offset0:24 offset1:28
	ds_read2_b32 v[172:173], v96 offset0:32 offset1:36
	ds_read2_b32 v[174:175], v96 offset0:40 offset1:44
	ds_read2_b32 v[176:177], v96 offset0:48 offset1:52
	ds_read2_b32 v[178:179], v96 offset0:56 offset1:60
	ds_read2_b32 v[180:181], v96 offset0:64 offset1:68
	ds_read2_b32 v[182:183], v96 offset0:72 offset1:76
	ds_read2_b32 v[184:185], v96 offset0:80 offset1:84
	ds_read2_b32 v[186:187], v96 offset0:88 offset1:92
	ds_read2_b32 v[188:189], v96 offset0:96 offset1:100
	ds_read2_b32 v[190:191], v96 offset0:104 offset1:108
	ds_read2_b32 v[192:193], v96 offset0:112 offset1:116
	s_nop 0
	s_nop 0
	s_waitcnt lgkmcnt(14)
	v_mfma_f32_16x16x4_f32 v[40:43], v98, v164, 0
	ds_read2_b32 v[194:195], v96 offset0:120 offset1:124
	s_nop 0
	s_nop 0
	v_mfma_f32_16x16x4_f32 v[144:147], v99, v165, 0
	s_nop 0
	s_waitcnt lgkmcnt(14)
	v_mfma_f32_16x16x4_f32 v[148:151], v100, v166, 0
	v_mfma_f32_16x16x4_f32 v[152:155], v101, v167, 0
	s_nop 0
	s_waitcnt lgkmcnt(13)
	v_mfma_f32_16x16x4_f32 v[40:43], v102, v168, v[40:43]
	v_mfma_f32_16x16x4_f32 v[144:147], v103, v169, v[144:147]
	s_nop 0
	s_nop 0
	s_waitcnt lgkmcnt(12)
	v_mfma_f32_16x16x4_f32 v[148:151], v104, v170, v[148:151]
	v_mfma_f32_16x16x4_f32 v[152:155], v105, v171, v[152:155]
	s_nop 0
	s_nop 0
	s_waitcnt lgkmcnt(11)
	v_mfma_f32_16x16x4_f32 v[40:43], v106, v172, v[40:43]
	v_mfma_f32_16x16x4_f32 v[144:147], v107, v173, v[144:147]
	s_nop 0
	s_nop 0
	s_waitcnt lgkmcnt(10)
	v_mfma_f32_16x16x4_f32 v[148:151], v108, v174, v[148:151]
	v_mfma_f32_16x16x4_f32 v[152:155], v109, v175, v[152:155]
	s_nop 0
	s_nop 0
	s_waitcnt lgkmcnt(9)
	v_mfma_f32_16x16x4_f32 v[40:43], v110, v176, v[40:43]
	v_mfma_f32_16x16x4_f32 v[144:147], v111, v177, v[144:147]
	s_nop 0
	s_nop 0
	s_waitcnt lgkmcnt(8)
	v_mfma_f32_16x16x4_f32 v[148:151], v112, v178, v[148:151]
	v_mfma_f32_16x16x4_f32 v[152:155], v113, v179, v[152:155]
	s_nop 0
	s_nop 0
	s_waitcnt lgkmcnt(7)
	v_mfma_f32_16x16x4_f32 v[40:43], v75, v180, v[40:43]
	v_mfma_f32_16x16x4_f32 v[144:147], v114, v181, v[144:147]
	s_nop 0
	s_nop 0
	s_waitcnt lgkmcnt(6)
	v_mfma_f32_16x16x4_f32 v[148:151], v115, v182, v[148:151]
	v_mfma_f32_16x16x4_f32 v[152:155], v116, v183, v[152:155]
	s_nop 0
	s_nop 0
	s_waitcnt lgkmcnt(5)
	v_mfma_f32_16x16x4_f32 v[40:43], v117, v184, v[40:43]
	v_mfma_f32_16x16x4_f32 v[144:147], v118, v185, v[144:147]
	s_nop 0
	s_nop 0
	s_waitcnt lgkmcnt(4)
	v_mfma_f32_16x16x4_f32 v[148:151], v119, v186, v[148:151]
	v_mfma_f32_16x16x4_f32 v[152:155], v120, v187, v[152:155]
	s_nop 0
	s_nop 0
	s_waitcnt lgkmcnt(3)
	v_mfma_f32_16x16x4_f32 v[40:43], v121, v188, v[40:43]
	v_mfma_f32_16x16x4_f32 v[144:147], v122, v189, v[144:147]
	s_nop 0
	s_nop 0
	s_waitcnt lgkmcnt(2)
	v_mfma_f32_16x16x4_f32 v[148:151], v123, v190, v[148:151]
	v_mfma_f32_16x16x4_f32 v[152:155], v124, v191, v[152:155]
	s_nop 0
	s_nop 0
	s_waitcnt lgkmcnt(1)
	v_mfma_f32_16x16x4_f32 v[40:43], v125, v192, v[40:43]
	v_mfma_f32_16x16x4_f32 v[144:147], v126, v193, v[144:147]
	s_nop 0
	s_nop 0
	s_waitcnt lgkmcnt(0)
	v_mfma_f32_16x16x4_f32 v[148:151], v127, v194, v[148:151]
	s_nop 6
	v_add_f32_e64 v146, v42, v146
	v_add_f32_e64 v147, v43, v147
	v_add_f32_e64 v144, v40, v144
	v_add_f32_e64 v145, v41, v145
	v_mfma_f32_16x16x4_f32 v[40:43], v128, v195, v[152:155]
	s_nop 9
	v_pk_add_f32 v[40:41], v[148:149], v[40:41]
	v_pk_add_f32 v[42:43], v[150:151], v[42:43]
	v_pk_add_f32 v[40:41], v[144:145], v[40:41]
	v_lshlrev_b32_e32 v144, 16, v92
	v_and_b32_e32 v145, 0xffff0000, v92
	v_pk_fma_f32 v[40:41], v[32:33], v[144:145], v[40:41]
	v_pk_add_f32 v[42:43], v[146:147], v[42:43]
	v_fma_f32 v92, |v40|, s57, 1.0
	v_rcp_f32_e32 v144, v92
	v_fma_f32 v92, |v41|, s57, 1.0
	v_rcp_f32_e32 v145, v92
	v_pk_mul_f32 v[146:147], v[40:41], v[40:41]
	v_mov_b64_e32 v[148:149], s[0:1]
	v_mul_f32_e32 v92, 0xbf38aa3b, v146
	v_exp_f32_e32 v146, v92
	v_pk_fma_f32 v[150:151], v[144:145], s[60:61], v[148:149] op_sel_hi:[1,0,0]
	v_mul_f32_e32 v92, 0xbf38aa3b, v147
	v_pk_fma_f32 v[150:151], v[144:145], v[150:151], s[62:63] op_sel_hi:[1,1,0]
	v_exp_f32_e32 v147, v92
	v_pk_fma_f32 v[150:151], v[144:145], v[150:151], s[64:65] op_sel_hi:[1,1,0]
	v_cmp_gt_f32_e32 vcc, 0, v41
	v_pk_fma_f32 v[150:151], v[144:145], v[150:151], s[66:67] op_sel_hi:[1,1,0]
	s_nop 0
	v_pk_mul_f32 v[144:145], v[144:145], v[150:151]
	s_nop 0
	v_pk_mul_f32 v[144:145], v[146:147], v[144:145]
	s_nop 0
	v_pk_mul_f32 v[146:147], v[40:41], v[144:145]
	v_pk_fma_f32 v[144:145], v[40:41], v[144:145], v[40:41] neg_lo:[1,0,0] neg_hi:[1,0,0]
	v_and_b32_e32 v41, 0xffff0000, v93
	v_cndmask_b32_e32 v129, v145, v147, vcc
	v_cmp_gt_f32_e32 vcc, 0, v40
	v_lshlrev_b32_e32 v40, 16, v93
	v_pk_fma_f32 v[40:41], v[34:35], v[40:41], v[42:43]
	v_cndmask_b32_e32 v146, v144, v146, vcc
	v_fma_f32 v42, |v40|, s57, 1.0
	v_fma_f32 v43, |v41|, s57, 1.0
	v_rcp_f32_e32 v42, v42
	v_rcp_f32_e32 v43, v43
	v_pk_mul_f32 v[92:93], v[40:41], v[40:41]
	v_cmp_gt_f32_e32 vcc, 0, v41
	v_mul_f32_e32 v92, 0xbf38aa3b, v92
	v_pk_fma_f32 v[144:145], v[42:43], s[60:61], v[148:149] op_sel_hi:[1,0,0]
	v_mul_f32_e32 v93, 0xbf38aa3b, v93
	v_exp_f32_e32 v92, v92
	v_pk_fma_f32 v[144:145], v[42:43], v[144:145], s[62:63] op_sel_hi:[1,1,0]
	v_exp_f32_e32 v93, v93
	v_pk_fma_f32 v[144:145], v[42:43], v[144:145], s[64:65] op_sel_hi:[1,1,0]
	s_nop 0
	v_pk_fma_f32 v[144:145], v[42:43], v[144:145], s[66:67] op_sel_hi:[1,1,0]
	s_nop 0
	v_pk_mul_f32 v[42:43], v[42:43], v[144:145]
	s_nop 0
	v_pk_mul_f32 v[42:43], v[92:93], v[42:43]
	s_nop 0
	v_pk_mul_f32 v[92:93], v[40:41], v[42:43]
	v_pk_fma_f32 v[42:43], v[40:41], v[42:43], v[40:41] neg_lo:[1,0,0] neg_hi:[1,0,0]
	s_nop 0
	v_cndmask_b32_e32 v41, v43, v93, vcc
	v_cmp_gt_f32_e32 vcc, 0, v40
	v_or_b32_e32 v43, v79, v89
	v_cvt_pk_bf16_f32 v40, v146, v129
	v_cndmask_b32_e32 v42, v42, v92, vcc
	v_cvt_pk_bf16_f32 v41, v42, v41
	v_or_b32_e32 v42, v78, v88
	v_lshlrev_b64 v[42:43], 10, v[42:43]
	v_lshl_add_u64 v[42:43], v[76:77], 0, v[42:43]
	global_store_dwordx2 v[42:43], v[40:41], off
	s_waitcnt lgkmcnt(0)
	s_waitcnt vmcnt(2)
	v_mov_b64_e32 v[42:43], v[38:39]
	v_lshl_add_u64 v[88:89], v[88:89], 0, 16
	v_mov_b64_e32 v[40:41], v[36:37]
	s_waitcnt vmcnt(1)
	v_mov_b64_e32 v[92:93], v[90:91]
	s_cbranch_scc1 .LBB0_275
